# attention: half-stage stagger of the two sub-head wave groups (2 barriers per 128-key stage), row-max folded into QK(b) slots; conv_bc rewritten with 2 channels per lane and batched row loads
# speedup vs baseline: 1.0910x; 1.0147x over previous
.LBB0_111:
	v_and_b32_e32 v170, 63, v4
	v_lshlrev_b32_e32 v2, 3, v5
	s_and_b32 s12, s5, 0xffffe000
	v_lshlrev_b32_e32 v172, 2, v5
	v_lshrrev_b32_e32 v3, 2, v4
	v_lshlrev_b32_e32 v5, 1, v4
	v_lshlrev_b32_e32 v4, 3, v4
	v_or_b32_e32 v2, s2, v2
	v_and_or_b32 v3, v3, 3, v172
	v_and_b32_e32 v5, 32, v5
	v_and_b32_e32 v4, 24, v4
	v_add_u32_e32 v0, s12, v0
	v_mov_b32_e32 v14, v1
	v_mov_b32_e32 v15, v1
	s_lshl_b32 s3, s10, 1
	s_lshr_b32 s13, s8, 1
	v_mul_u32_u24_e32 v171, 0x110, v6
	v_mad_u32_u24 v178, v6, s26, 0
	v_add3_u32 v179, s16, v5, v4
	v_lshlrev_b32_e32 v180, 1, v2
	v_mul_u32_u24_e32 v181, 0x100, v3
	v_add_u32_e32 v179, v179, v181
	v_and_b32_e32 v181, 3, v3
	v_lshl_add_u32 v179, v181, 6, v179
	v_add_u32_e32 v164, 0x160, v0
	v_mov_b32_e32 v0, v1
	v_mov_b32_e32 v2, v1
	v_mov_b32_e32 v3, v1
	v_mov_b32_e32 v4, v1
	v_mov_b32_e32 v5, v1
	v_mov_b32_e32 v6, v1
	v_mov_b32_e32 v7, v1
	v_mov_b32_e32 v8, v1
	v_mov_b32_e32 v9, v1
	v_mov_b32_e32 v10, v1
	v_mov_b32_e32 v11, v1
	v_mov_b32_e32 v12, v1
	v_mov_b32_e32 v13, v1
	v_mov_b64_e32 v[30:31], v[14:15]
	v_mov_b64_e32 v[46:47], v[14:15]
	v_mov_b64_e32 v[62:63], v[14:15]
	v_mov_b64_e32 v[78:79], v[14:15]
	s_or_b32 s3, s13, s3
	s_mov_b32 s2, 0
	v_mov_b32_e32 v183, 0xf149f2ca
	v_mov_b32_e32 v182, 0
	v_mov_b64_e32 v[28:29], v[12:13]
	v_mov_b64_e32 v[26:27], v[10:11]
	v_mov_b64_e32 v[24:25], v[8:9]
	v_mov_b64_e32 v[22:23], v[6:7]
	v_mov_b64_e32 v[20:21], v[4:5]
	v_mov_b64_e32 v[18:19], v[2:3]
	v_mov_b64_e32 v[16:17], v[0:1]
	v_mov_b64_e32 v[44:45], v[12:13]
	v_mov_b64_e32 v[42:43], v[10:11]
	v_mov_b64_e32 v[40:41], v[8:9]
	v_mov_b64_e32 v[38:39], v[6:7]
	v_mov_b64_e32 v[36:37], v[4:5]
	v_mov_b64_e32 v[34:35], v[2:3]
	v_mov_b64_e32 v[32:33], v[0:1]
	v_mov_b64_e32 v[60:61], v[12:13]
	v_mov_b64_e32 v[58:59], v[10:11]
	v_mov_b64_e32 v[56:57], v[8:9]
	v_mov_b64_e32 v[54:55], v[6:7]
	v_mov_b64_e32 v[52:53], v[4:5]
	v_mov_b64_e32 v[50:51], v[2:3]
	v_mov_b64_e32 v[48:49], v[0:1]
	v_mov_b64_e32 v[76:77], v[12:13]
	v_mov_b64_e32 v[74:75], v[10:11]
	v_mov_b64_e32 v[72:73], v[8:9]
	v_mov_b64_e32 v[70:71], v[6:7]
	v_mov_b64_e32 v[68:69], v[4:5]
	v_mov_b64_e32 v[66:67], v[2:3]
	v_mov_b64_e32 v[64:65], v[0:1]
	s_mov_b32 s12, 0
	s_waitcnt lgkmcnt(0)
	s_barrier
	s_cmp_eq_u32 s11, 1
	s_cbranch_scc0 .Lattn_skip_b1
	s_barrier
.Lattn_skip_b1:
	s_add_i32 s13, s12, 1
	s_branch .LBB0_116

.LBB0_120:
	s_barrier
	v_mov_b32_e32 v183, v7
	s_branch .LBB0_125
.Lattn_pair:
	s_cmp_eq_u32 s11, 1
	s_cbranch_scc0 .Lattn_pair_g0
	s_cmp_ge_u32 s12, s10
	s_cbranch_scc1 .Lattn_pair_g0
	s_and_b32 s14, s13, 1
	s_mul_i32 s15, s14, 0x8800
	s_mul_i32 s14, s14, 0x9000
	v_add3_u32 v2, v176, s15, v174
	v_add3_u32 v3, v177, s14, v175
	s_waitcnt vmcnt(7)
	ds_write_b128 v2, v[128:131]
	s_waitcnt vmcnt(6)
	ds_write_b128 v3, v[132:135]
	s_waitcnt vmcnt(5)
	ds_write_b128 v2, v[136:139] offset:8704
	s_waitcnt vmcnt(4)
	ds_write_b128 v3, v[140:143] offset:8192
	s_waitcnt vmcnt(3)
	ds_write_b128 v2, v[144:147] offset:17408
	s_waitcnt vmcnt(2)
	ds_write_b128 v3, v[148:151] offset:16384
	s_waitcnt vmcnt(1)
	ds_write_b128 v2, v[152:155] offset:26112
	s_waitcnt vmcnt(0)
	ds_write_b128 v3, v[156:159] offset:24576
	s_add_i32 s14, s12, 2
	s_cmp_gt_u32 s14, s10
	s_cbranch_scc1 .Lattn_pair_g0
	v_lshlrev_b32_e32 v4, 1, v173
	v_lshl_add_u32 v4, v164, 11, v4
	v_add_u32_e32 v5, 0xfffd0000, v4
	global_load_dwordx4 v[128:131], v5, s[86:87]
	global_load_dwordx4 v[132:135], v5, s[88:89]
	v_add_u32_e32 v5, 0xfffe0000, v4
	global_load_dwordx4 v[136:139], v5, s[86:87]
	global_load_dwordx4 v[140:143], v5, s[88:89]
	v_add_u32_e32 v5, 0xffff0000, v4
	global_load_dwordx4 v[144:147], v5, s[86:87]
	global_load_dwordx4 v[148:151], v5, s[88:89]
	v_mov_b32_e32 v5, v4
	global_load_dwordx4 v[152:155], v5, s[86:87]
	global_load_dwordx4 v[156:159], v5, s[88:89]
.Lattn_pair_g0:
	v_xor_b32_e32 v225, 64, v0
	v_xor_b32_e32 v248, 0xc0, v0
	ds_read_b128 v[2:5], v6
	ds_read_b128 v[8:11], v6 offset:8704
	ds_read_b128 v[12:15], v6 offset:32
	ds_read_b128 v[226:229], v6 offset:8736
	s_waitcnt lgkmcnt(3)
	v_mfma_f32_32x32x16_bf16 v[96:111], v[2:5], v[112:115], 0
	ds_read_b128 v[2:5], v6 offset:64
	s_waitcnt lgkmcnt(3)
	v_mfma_f32_32x32x16_bf16 v[80:95], v[8:11], v[112:115], 0
	ds_read_b128 v[8:11], v6 offset:8768
	s_waitcnt lgkmcnt(3)
	v_mfma_f32_32x32x16_bf16 v[96:111], v[12:15], v[116:119], v[96:111]
	ds_read_b128 v[12:15], v6 offset:96
	s_waitcnt lgkmcnt(3)
	v_mfma_f32_32x32x16_bf16 v[80:95], v[226:229], v[116:119], v[80:95]
	ds_read_b128 v[226:229], v6 offset:8800
	s_waitcnt lgkmcnt(3)
	v_mfma_f32_32x32x16_bf16 v[96:111], v[2:5], v[120:123], v[96:111]
	ds_read_b128 v[2:5], v6 offset:17408
	s_waitcnt lgkmcnt(3)
	v_mfma_f32_32x32x16_bf16 v[80:95], v[8:11], v[120:123], v[80:95]
	ds_read_b128 v[8:11], v6 offset:26112
	s_waitcnt lgkmcnt(3)
	v_mfma_f32_32x32x16_bf16 v[96:111], v[12:15], v[124:127], v[96:111]
	ds_read_b128 v[12:15], v6 offset:17440
	s_waitcnt lgkmcnt(3)
	v_mfma_f32_32x32x16_bf16 v[80:95], v[226:229], v[124:127], v[80:95]
	ds_read_b128 v[226:229], v6 offset:26144
	s_waitcnt lgkmcnt(3)
	v_mfma_f32_32x32x16_bf16 v[184:199], v[2:5], v[112:115], 0
	ds_read_b128 v[2:5], v6 offset:17472
	s_nop 7
	v_max3_f32 v238, v96, v97, v98
	v_max3_f32 v241, v99, v100, v101
	v_max3_f32 v246, v102, v103, v104
	v_max3_f32 v247, v105, v106, v107
	v_max3_f32 v238, v238, v108, v109
	v_max3_f32 v241, v241, v110, v111
	v_max3_f32 v246, v246, v80, v81
	v_max3_f32 v247, v247, v82, v83
	s_waitcnt lgkmcnt(3)
	v_mfma_f32_32x32x16_bf16 v[200:215], v[8:11], v[112:115], 0
	ds_read_b128 v[8:11], v6 offset:26176
	v_max3_f32 v238, v238, v84, v85
	v_max3_f32 v241, v241, v86, v87
	v_max3_f32 v246, v246, v88, v89
	v_max3_f32 v247, v247, v90, v91
	v_max3_f32 v238, v238, v92, v93
	v_max3_f32 v241, v241, v94, v95
	v_max3_f32 v238, v238, v241, v246
	v_max_f32_e32 v238, v238, v247
	v_and_b32_e32 v246, 64, v220
	v_xor_b32_e32 v247, 32, v220
	v_add_u32_e32 v246, 64, v246
	v_cmp_lt_i32_e32 vcc, v247, v246
	s_nop 1
	v_cndmask_b32_e32 v247, v220, v247, vcc
	v_lshlrev_b32_e32 v247, 2, v247
	ds_bpermute_b32 v241, v247, v238
	s_waitcnt lgkmcnt(4)
	v_mfma_f32_32x32x16_bf16 v[184:199], v[12:15], v[116:119], v[184:199]
	ds_read_b128 v[12:15], v6 offset:17504
	s_waitcnt lgkmcnt(1)
	v_max3_f32 v7, v183, v238, v241
	v_cmp_gt_f32_e32 vcc, v7, v183
	s_cbranch_vccz .Lattn_pair_nra
	v_sub_f32_e32 v246, v183, v7
	v_mul_f32_e32 v246, 0x3e38aa3b, v246
	v_exp_f32_e32 v246, v246
	s_nop 0
	v_pk_mul_f32 v[78:79], v[78:79], v[246:247] op_sel_hi:[1,0]
	v_pk_mul_f32 v[76:77], v[76:77], v[246:247] op_sel_hi:[1,0]
	v_pk_mul_f32 v[74:75], v[74:75], v[246:247] op_sel_hi:[1,0]
	v_pk_mul_f32 v[72:73], v[72:73], v[246:247] op_sel_hi:[1,0]
	v_pk_mul_f32 v[70:71], v[70:71], v[246:247] op_sel_hi:[1,0]
	v_pk_mul_f32 v[68:69], v[68:69], v[246:247] op_sel_hi:[1,0]
	v_pk_mul_f32 v[66:67], v[66:67], v[246:247] op_sel_hi:[1,0]
	v_pk_mul_f32 v[64:65], v[64:65], v[246:247] op_sel_hi:[1,0]
	v_pk_mul_f32 v[62:63], v[62:63], v[246:247] op_sel_hi:[1,0]
	v_pk_mul_f32 v[60:61], v[60:61], v[246:247] op_sel_hi:[1,0]
	v_pk_mul_f32 v[58:59], v[58:59], v[246:247] op_sel_hi:[1,0]
	v_pk_mul_f32 v[56:57], v[56:57], v[246:247] op_sel_hi:[1,0]
	v_pk_mul_f32 v[54:55], v[54:55], v[246:247] op_sel_hi:[1,0]
	v_pk_mul_f32 v[52:53], v[52:53], v[246:247] op_sel_hi:[1,0]
	v_pk_mul_f32 v[50:51], v[50:51], v[246:247] op_sel_hi:[1,0]
	v_pk_mul_f32 v[48:49], v[48:49], v[246:247] op_sel_hi:[1,0]
	v_pk_mul_f32 v[46:47], v[46:47], v[246:247] op_sel_hi:[1,0]
	v_pk_mul_f32 v[44:45], v[44:45], v[246:247] op_sel_hi:[1,0]
	v_pk_mul_f32 v[42:43], v[42:43], v[246:247] op_sel_hi:[1,0]
	v_pk_mul_f32 v[40:41], v[40:41], v[246:247] op_sel_hi:[1,0]
	v_pk_mul_f32 v[38:39], v[38:39], v[246:247] op_sel_hi:[1,0]
	v_pk_mul_f32 v[36:37], v[36:37], v[246:247] op_sel_hi:[1,0]
	v_pk_mul_f32 v[34:35], v[34:35], v[246:247] op_sel_hi:[1,0]
	v_pk_mul_f32 v[32:33], v[32:33], v[246:247] op_sel_hi:[1,0]
	v_pk_mul_f32 v[30:31], v[30:31], v[246:247] op_sel_hi:[1,0]
	v_pk_mul_f32 v[28:29], v[28:29], v[246:247] op_sel_hi:[1,0]
	v_pk_mul_f32 v[26:27], v[26:27], v[246:247] op_sel_hi:[1,0]
	v_pk_mul_f32 v[24:25], v[24:25], v[246:247] op_sel_hi:[1,0]
	v_pk_mul_f32 v[22:23], v[22:23], v[246:247] op_sel_hi:[1,0]
	v_pk_mul_f32 v[20:21], v[20:21], v[246:247] op_sel_hi:[1,0]
	v_pk_mul_f32 v[18:19], v[18:19], v[246:247] op_sel_hi:[1,0]
	v_pk_mul_f32 v[16:17], v[16:17], v[246:247] op_sel_hi:[1,0]
	v_mul_f32_e32 v182, v182, v246
.Lattn_pair_nra:
	v_mul_f32_e32 v165, 0xbe38aa3b, v7
	s_waitcnt lgkmcnt(4)
	v_mfma_f32_32x32x16_bf16 v[200:215], v[226:229], v[116:119], v[200:215]
	ds_read_b128 v[226:229], v6 offset:26208
	v_fmamk_f32 v96, v96, 0x3e38aa3b, v165
	v_fmamk_f32 v97, v97, 0x3e38aa3b, v165
	v_fmamk_f32 v98, v98, 0x3e38aa3b, v165
	v_fmamk_f32 v99, v99, 0x3e38aa3b, v165
	v_exp_f32_e32 v96, v96
	v_exp_f32_e32 v97, v97
	v_exp_f32_e32 v98, v98
	v_exp_f32_e32 v99, v99
	v_add_f32_e32 v238, v96, v97
	v_add_f32_e32 v241, v98, v99
	v_cvt_pk_bf16_f32 v96, v96, v97
	v_cvt_pk_bf16_f32 v97, v98, v99
	s_waitcnt lgkmcnt(4)
	v_mfma_f32_32x32x16_bf16 v[184:199], v[2:5], v[120:123], v[184:199]
	v_xor_b32_e32 v6, 0x80, v0
	ds_read_b64_tr_b16 v[230:231], v0
	ds_read_b64_tr_b16 v[232:233], v0 offset:2048
	v_fmamk_f32 v100, v100, 0x3e38aa3b, v165
	v_fmamk_f32 v101, v101, 0x3e38aa3b, v165
	v_fmamk_f32 v102, v102, 0x3e38aa3b, v165
	v_fmamk_f32 v103, v103, 0x3e38aa3b, v165
	v_exp_f32_e32 v100, v100
	v_exp_f32_e32 v101, v101
	v_exp_f32_e32 v102, v102
	v_exp_f32_e32 v103, v103
	v_add_f32_e32 v246, v100, v101
	v_add_f32_e32 v247, v102, v103
	v_add_f32_e32 v238, v238, v246
	v_add_f32_e32 v241, v241, v247
	v_cvt_pk_bf16_f32 v98, v100, v101
	v_cvt_pk_bf16_f32 v99, v102, v103
	s_waitcnt lgkmcnt(5)
	v_mfma_f32_32x32x16_bf16 v[200:215], v[8:11], v[120:123], v[200:215]
	ds_read_b64_tr_b16 v[234:235], v225
	ds_read_b64_tr_b16 v[236:237], v225 offset:2048
	v_fmamk_f32 v104, v104, 0x3e38aa3b, v165
	v_fmamk_f32 v105, v105, 0x3e38aa3b, v165
	v_fmamk_f32 v106, v106, 0x3e38aa3b, v165
	v_fmamk_f32 v107, v107, 0x3e38aa3b, v165
	v_exp_f32_e32 v104, v104
	v_exp_f32_e32 v105, v105
	v_exp_f32_e32 v106, v106
	v_exp_f32_e32 v107, v107
	v_add_f32_e32 v246, v104, v105
	v_add_f32_e32 v247, v106, v107
	v_add_f32_e32 v238, v238, v246
	v_add_f32_e32 v241, v241, v247
	v_cvt_pk_bf16_f32 v104, v104, v105
	v_cvt_pk_bf16_f32 v105, v106, v107
	s_waitcnt lgkmcnt(5)
	v_mfma_f32_32x32x16_bf16 v[184:199], v[12:15], v[124:127], v[184:199]
	ds_read_b64_tr_b16 v[242:243], v6
	ds_read_b64_tr_b16 v[244:245], v6 offset:2048
	v_fmamk_f32 v108, v108, 0x3e38aa3b, v165
	v_fmamk_f32 v109, v109, 0x3e38aa3b, v165
	v_fmamk_f32 v110, v110, 0x3e38aa3b, v165
	v_fmamk_f32 v111, v111, 0x3e38aa3b, v165
	v_exp_f32_e32 v108, v108
	v_exp_f32_e32 v109, v109
	v_exp_f32_e32 v110, v110
	v_exp_f32_e32 v111, v111
	v_add_f32_e32 v246, v108, v109
	v_add_f32_e32 v247, v110, v111
	v_add_f32_e32 v238, v238, v246
	v_add_f32_e32 v241, v241, v247
	v_cvt_pk_bf16_f32 v106, v108, v109
	v_cvt_pk_bf16_f32 v107, v110, v111
	s_waitcnt lgkmcnt(6)
	v_mfma_f32_32x32x16_bf16 v[200:215], v[226:229], v[124:127], v[200:215]
	ds_read_b64_tr_b16 v[2:3], v248
	ds_read_b64_tr_b16 v[4:5], v248 offset:2048
	v_fmamk_f32 v80, v80, 0x3e38aa3b, v165
	v_fmamk_f32 v81, v81, 0x3e38aa3b, v165
	v_fmamk_f32 v82, v82, 0x3e38aa3b, v165
	v_fmamk_f32 v83, v83, 0x3e38aa3b, v165
	v_exp_f32_e32 v80, v80
	v_exp_f32_e32 v81, v81
	v_exp_f32_e32 v82, v82
	v_exp_f32_e32 v83, v83
	v_add_f32_e32 v246, v80, v81
	v_add_f32_e32 v247, v82, v83
	v_add_f32_e32 v238, v238, v246
	v_add_f32_e32 v241, v241, v247
	v_cvt_pk_bf16_f32 v80, v80, v81
	v_cvt_pk_bf16_f32 v81, v82, v83
	s_barrier
	s_waitcnt lgkmcnt(6)
	v_mfma_f32_32x32x16_bf16 v[64:79], v[230:233], v[96:99], v[64:79]
	ds_read_b64_tr_b16 v[8:9], v0 offset:4096
	ds_read_b64_tr_b16 v[10:11], v0 offset:6144
	v_fmamk_f32 v84, v84, 0x3e38aa3b, v165
	v_fmamk_f32 v85, v85, 0x3e38aa3b, v165
	v_fmamk_f32 v86, v86, 0x3e38aa3b, v165
	v_fmamk_f32 v87, v87, 0x3e38aa3b, v165
	v_exp_f32_e32 v84, v84
	v_exp_f32_e32 v85, v85
	v_exp_f32_e32 v86, v86
	v_exp_f32_e32 v87, v87
	v_add_f32_e32 v246, v84, v85
	v_add_f32_e32 v247, v86, v87
	v_add_f32_e32 v238, v238, v246
	v_add_f32_e32 v241, v241, v247
	v_cvt_pk_bf16_f32 v82, v84, v85
	v_cvt_pk_bf16_f32 v83, v86, v87
	s_waitcnt lgkmcnt(6)
	v_mfma_f32_32x32x16_bf16 v[48:63], v[234:237], v[96:99], v[48:63]
	ds_read_b64_tr_b16 v[12:13], v225 offset:4096
	ds_read_b64_tr_b16 v[14:15], v225 offset:6144
	v_fmamk_f32 v88, v88, 0x3e38aa3b, v165
	v_fmamk_f32 v89, v89, 0x3e38aa3b, v165
	v_fmamk_f32 v90, v90, 0x3e38aa3b, v165
	v_fmamk_f32 v91, v91, 0x3e38aa3b, v165
	v_exp_f32_e32 v88, v88
	v_exp_f32_e32 v89, v89
	v_exp_f32_e32 v90, v90
	v_exp_f32_e32 v91, v91
	v_add_f32_e32 v246, v88, v89
	v_add_f32_e32 v247, v90, v91
	v_add_f32_e32 v238, v238, v246
	v_add_f32_e32 v241, v241, v247
	v_cvt_pk_bf16_f32 v88, v88, v89
	v_cvt_pk_bf16_f32 v89, v90, v91
	s_waitcnt lgkmcnt(6)
	v_mfma_f32_32x32x16_bf16 v[32:47], v[242:245], v[96:99], v[32:47]
	ds_read_b64_tr_b16 v[226:227], v6 offset:4096
	ds_read_b64_tr_b16 v[228:229], v6 offset:6144
	v_fmamk_f32 v92, v92, 0x3e38aa3b, v165
	v_fmamk_f32 v93, v93, 0x3e38aa3b, v165
	v_fmamk_f32 v94, v94, 0x3e38aa3b, v165
	v_fmamk_f32 v95, v95, 0x3e38aa3b, v165
	v_exp_f32_e32 v92, v92
	v_exp_f32_e32 v93, v93
	v_exp_f32_e32 v94, v94
	v_exp_f32_e32 v95, v95
	v_add_f32_e32 v246, v92, v93
	v_add_f32_e32 v247, v94, v95
	v_add_f32_e32 v238, v238, v246
	v_add_f32_e32 v241, v241, v247
	v_cvt_pk_bf16_f32 v90, v92, v93
	v_cvt_pk_bf16_f32 v91, v94, v95
	v_add_f32_e32 v238, v238, v241
	v_add_f32_e32 v182, v182, v238
	s_waitcnt lgkmcnt(6)
	v_mfma_f32_32x32x16_bf16 v[16:31], v[2:5], v[96:99], v[16:31]
	ds_read_b64_tr_b16 v[230:231], v248 offset:4096
	ds_read_b64_tr_b16 v[232:233], v248 offset:6144
	v_max3_f32 v238, v184, v185, v186
	v_max3_f32 v241, v187, v188, v189
	v_max3_f32 v246, v190, v191, v192
	v_max3_f32 v247, v193, v194, v195
	v_max3_f32 v238, v238, v196, v197
	v_max3_f32 v241, v241, v198, v199
	v_max3_f32 v246, v246, v200, v201
	v_max3_f32 v247, v247, v202, v203
	s_waitcnt lgkmcnt(6)
	v_mfma_f32_32x32x16_bf16 v[64:79], v[8:11], v[104:107], v[64:79]
	ds_read_b64_tr_b16 v[234:235], v0 offset:8192
	ds_read_b64_tr_b16 v[236:237], v0 offset:10240
	v_max3_f32 v238, v238, v204, v205
	v_max3_f32 v241, v241, v206, v207
	v_max3_f32 v246, v246, v208, v209
	v_max3_f32 v247, v247, v210, v211
	v_max3_f32 v238, v238, v212, v213
	v_max3_f32 v241, v241, v214, v215
	v_max3_f32 v238, v238, v241, v246
	v_max_f32_e32 v238, v238, v247
	v_and_b32_e32 v246, 64, v220
	v_xor_b32_e32 v247, 32, v220
	v_add_u32_e32 v246, 64, v246
	v_cmp_lt_i32_e32 vcc, v247, v246
	s_nop 1
	v_cndmask_b32_e32 v247, v220, v247, vcc
	v_lshlrev_b32_e32 v247, 2, v247
	ds_bpermute_b32 v241, v247, v238
	s_waitcnt lgkmcnt(7)
	v_mfma_f32_32x32x16_bf16 v[48:63], v[12:15], v[104:107], v[48:63]
	ds_read_b64_tr_b16 v[242:243], v225 offset:8192
	ds_read_b64_tr_b16 v[244:245], v225 offset:10240
	s_waitcnt lgkmcnt(7)
	v_mfma_f32_32x32x16_bf16 v[32:47], v[226:229], v[104:107], v[32:47]
	ds_read_b64_tr_b16 v[2:3], v6 offset:8192
	ds_read_b64_tr_b16 v[4:5], v6 offset:10240
	s_waitcnt lgkmcnt(4)
	v_max3_f32 v183, v7, v238, v241
	v_mul_f32_e32 v165, 0xbe38aa3b, v183
	s_waitcnt lgkmcnt(7)
	v_mfma_f32_32x32x16_bf16 v[16:31], v[230:233], v[104:107], v[16:31]
	ds_read_b64_tr_b16 v[8:9], v248 offset:8192
	ds_read_b64_tr_b16 v[10:11], v248 offset:10240
	v_fmamk_f32 v184, v184, 0x3e38aa3b, v165
	v_fmamk_f32 v185, v185, 0x3e38aa3b, v165
	v_fmamk_f32 v186, v186, 0x3e38aa3b, v165
	v_fmamk_f32 v187, v187, 0x3e38aa3b, v165
	v_exp_f32_e32 v184, v184
	v_exp_f32_e32 v185, v185
	v_exp_f32_e32 v186, v186
	v_exp_f32_e32 v187, v187
	v_add_f32_e32 v238, v184, v185
	v_add_f32_e32 v241, v186, v187
	v_cvt_pk_bf16_f32 v184, v184, v185
	v_cvt_pk_bf16_f32 v185, v186, v187
	s_waitcnt lgkmcnt(7)
	v_mfma_f32_32x32x16_bf16 v[64:79], v[234:237], v[80:83], v[64:79]
	ds_read_b64_tr_b16 v[12:13], v0 offset:12288
	ds_read_b64_tr_b16 v[14:15], v0 offset:14336
	v_fmamk_f32 v188, v188, 0x3e38aa3b, v165
	v_fmamk_f32 v189, v189, 0x3e38aa3b, v165
	v_fmamk_f32 v190, v190, 0x3e38aa3b, v165
	v_fmamk_f32 v191, v191, 0x3e38aa3b, v165
	v_exp_f32_e32 v188, v188
	v_exp_f32_e32 v189, v189
	v_exp_f32_e32 v190, v190
	v_exp_f32_e32 v191, v191
	v_add_f32_e32 v246, v188, v189
	v_add_f32_e32 v247, v190, v191
	v_add_f32_e32 v238, v238, v246
	v_add_f32_e32 v241, v241, v247
	v_cvt_pk_bf16_f32 v186, v188, v189
	v_cvt_pk_bf16_f32 v187, v190, v191
	s_waitcnt lgkmcnt(6)
	v_mfma_f32_32x32x16_bf16 v[48:63], v[242:245], v[80:83], v[48:63]
	ds_read_b64_tr_b16 v[226:227], v225 offset:12288
	ds_read_b64_tr_b16 v[228:229], v225 offset:14336
	v_fmamk_f32 v192, v192, 0x3e38aa3b, v165
	v_fmamk_f32 v193, v193, 0x3e38aa3b, v165
	v_fmamk_f32 v194, v194, 0x3e38aa3b, v165
	v_fmamk_f32 v195, v195, 0x3e38aa3b, v165
	v_exp_f32_e32 v192, v192
	v_exp_f32_e32 v193, v193
	v_exp_f32_e32 v194, v194
	v_exp_f32_e32 v195, v195
	v_add_f32_e32 v246, v192, v193
	v_add_f32_e32 v247, v194, v195
	v_add_f32_e32 v238, v238, v246
	v_add_f32_e32 v241, v241, v247
	v_cvt_pk_bf16_f32 v192, v192, v193
	v_cvt_pk_bf16_f32 v193, v194, v195
	s_waitcnt lgkmcnt(6)
	v_mfma_f32_32x32x16_bf16 v[32:47], v[2:5], v[80:83], v[32:47]
	ds_read_b64_tr_b16 v[230:231], v6 offset:12288
	ds_read_b64_tr_b16 v[232:233], v6 offset:14336
	v_fmamk_f32 v196, v196, 0x3e38aa3b, v165
	v_fmamk_f32 v197, v197, 0x3e38aa3b, v165
	v_fmamk_f32 v198, v198, 0x3e38aa3b, v165
	v_fmamk_f32 v199, v199, 0x3e38aa3b, v165
	v_exp_f32_e32 v196, v196
	v_exp_f32_e32 v197, v197
	v_exp_f32_e32 v198, v198
	v_exp_f32_e32 v199, v199
	v_add_f32_e32 v246, v196, v197
	v_add_f32_e32 v247, v198, v199
	v_add_f32_e32 v238, v238, v246
	v_add_f32_e32 v241, v241, v247
	v_cvt_pk_bf16_f32 v194, v196, v197
	v_cvt_pk_bf16_f32 v195, v198, v199
	s_waitcnt lgkmcnt(6)
	v_mfma_f32_32x32x16_bf16 v[16:31], v[8:11], v[80:83], v[16:31]
	ds_read_b64_tr_b16 v[234:235], v248 offset:12288
	ds_read_b64_tr_b16 v[236:237], v248 offset:14336
	v_fmamk_f32 v200, v200, 0x3e38aa3b, v165
	v_fmamk_f32 v201, v201, 0x3e38aa3b, v165
	v_fmamk_f32 v202, v202, 0x3e38aa3b, v165
	v_fmamk_f32 v203, v203, 0x3e38aa3b, v165
	v_exp_f32_e32 v200, v200
	v_exp_f32_e32 v201, v201
	v_exp_f32_e32 v202, v202
	v_exp_f32_e32 v203, v203
	v_add_f32_e32 v246, v200, v201
	v_add_f32_e32 v247, v202, v203
	v_add_f32_e32 v238, v238, v246
	v_add_f32_e32 v241, v241, v247
	v_cvt_pk_bf16_f32 v200, v200, v201
	v_cvt_pk_bf16_f32 v201, v202, v203
	s_waitcnt lgkmcnt(6)
	v_mfma_f32_32x32x16_bf16 v[64:79], v[12:15], v[88:91], v[64:79]
	ds_read_b64_tr_b16 v[242:243], v0 offset:16384
	ds_read_b64_tr_b16 v[244:245], v0 offset:18432
	v_fmamk_f32 v204, v204, 0x3e38aa3b, v165
	v_fmamk_f32 v205, v205, 0x3e38aa3b, v165
	v_fmamk_f32 v206, v206, 0x3e38aa3b, v165
	v_fmamk_f32 v207, v207, 0x3e38aa3b, v165
	v_exp_f32_e32 v204, v204
	v_exp_f32_e32 v205, v205
	v_exp_f32_e32 v206, v206
	v_exp_f32_e32 v207, v207
	v_add_f32_e32 v246, v204, v205
	v_add_f32_e32 v247, v206, v207
	v_add_f32_e32 v238, v238, v246
	v_add_f32_e32 v241, v241, v247
	v_cvt_pk_bf16_f32 v202, v204, v205
	v_cvt_pk_bf16_f32 v203, v206, v207
	s_waitcnt lgkmcnt(6)
	v_mfma_f32_32x32x16_bf16 v[48:63], v[226:229], v[88:91], v[48:63]
	ds_read_b64_tr_b16 v[2:3], v225 offset:16384
	ds_read_b64_tr_b16 v[4:5], v225 offset:18432
	v_fmamk_f32 v208, v208, 0x3e38aa3b, v165
	v_fmamk_f32 v209, v209, 0x3e38aa3b, v165
	v_fmamk_f32 v210, v210, 0x3e38aa3b, v165
	v_fmamk_f32 v211, v211, 0x3e38aa3b, v165
	v_exp_f32_e32 v208, v208
	v_exp_f32_e32 v209, v209
	v_exp_f32_e32 v210, v210
	v_exp_f32_e32 v211, v211
	v_add_f32_e32 v246, v208, v209
	v_add_f32_e32 v247, v210, v211
	v_add_f32_e32 v238, v238, v246
	v_add_f32_e32 v241, v241, v247
	v_cvt_pk_bf16_f32 v208, v208, v209
	v_cvt_pk_bf16_f32 v209, v210, v211
	s_waitcnt lgkmcnt(6)
	v_mfma_f32_32x32x16_bf16 v[32:47], v[230:233], v[88:91], v[32:47]
	ds_read_b64_tr_b16 v[8:9], v6 offset:16384
	ds_read_b64_tr_b16 v[10:11], v6 offset:18432
	v_fmamk_f32 v212, v212, 0x3e38aa3b, v165
	v_fmamk_f32 v213, v213, 0x3e38aa3b, v165
	v_fmamk_f32 v214, v214, 0x3e38aa3b, v165
	v_fmamk_f32 v215, v215, 0x3e38aa3b, v165
	v_exp_f32_e32 v212, v212
	v_exp_f32_e32 v213, v213
	v_exp_f32_e32 v214, v214
	v_exp_f32_e32 v215, v215
	v_add_f32_e32 v246, v212, v213
	v_add_f32_e32 v247, v214, v215
	v_add_f32_e32 v238, v238, v246
	v_add_f32_e32 v241, v241, v247
	v_cvt_pk_bf16_f32 v210, v212, v213
	v_cvt_pk_bf16_f32 v211, v214, v215
	s_waitcnt lgkmcnt(6)
	v_mfma_f32_32x32x16_bf16 v[16:31], v[234:237], v[88:91], v[16:31]
	ds_read_b64_tr_b16 v[12:13], v248 offset:16384
	ds_read_b64_tr_b16 v[14:15], v248 offset:18432
	v_add_f32_e32 v238, v238, v241
	v_cmp_gt_f32_e32 vcc, v183, v7
	s_cbranch_vccz .Lattn_pair_nrb
	s_nop 15
	v_sub_f32_e32 v246, v7, v183
	v_mul_f32_e32 v246, 0x3e38aa3b, v246
	v_exp_f32_e32 v246, v246
	s_nop 0
	v_pk_mul_f32 v[78:79], v[78:79], v[246:247] op_sel_hi:[1,0]
	v_pk_mul_f32 v[76:77], v[76:77], v[246:247] op_sel_hi:[1,0]
	v_pk_mul_f32 v[74:75], v[74:75], v[246:247] op_sel_hi:[1,0]
	v_pk_mul_f32 v[72:73], v[72:73], v[246:247] op_sel_hi:[1,0]
	v_pk_mul_f32 v[70:71], v[70:71], v[246:247] op_sel_hi:[1,0]
	v_pk_mul_f32 v[68:69], v[68:69], v[246:247] op_sel_hi:[1,0]
	v_pk_mul_f32 v[66:67], v[66:67], v[246:247] op_sel_hi:[1,0]
	v_pk_mul_f32 v[64:65], v[64:65], v[246:247] op_sel_hi:[1,0]
	v_pk_mul_f32 v[62:63], v[62:63], v[246:247] op_sel_hi:[1,0]
	v_pk_mul_f32 v[60:61], v[60:61], v[246:247] op_sel_hi:[1,0]
	v_pk_mul_f32 v[58:59], v[58:59], v[246:247] op_sel_hi:[1,0]
	v_pk_mul_f32 v[56:57], v[56:57], v[246:247] op_sel_hi:[1,0]
	v_pk_mul_f32 v[54:55], v[54:55], v[246:247] op_sel_hi:[1,0]
	v_pk_mul_f32 v[52:53], v[52:53], v[246:247] op_sel_hi:[1,0]
	v_pk_mul_f32 v[50:51], v[50:51], v[246:247] op_sel_hi:[1,0]
	v_pk_mul_f32 v[48:49], v[48:49], v[246:247] op_sel_hi:[1,0]
	v_pk_mul_f32 v[46:47], v[46:47], v[246:247] op_sel_hi:[1,0]
	v_pk_mul_f32 v[44:45], v[44:45], v[246:247] op_sel_hi:[1,0]
	v_pk_mul_f32 v[42:43], v[42:43], v[246:247] op_sel_hi:[1,0]
	v_pk_mul_f32 v[40:41], v[40:41], v[246:247] op_sel_hi:[1,0]
	v_pk_mul_f32 v[38:39], v[38:39], v[246:247] op_sel_hi:[1,0]
	v_pk_mul_f32 v[36:37], v[36:37], v[246:247] op_sel_hi:[1,0]
	v_pk_mul_f32 v[34:35], v[34:35], v[246:247] op_sel_hi:[1,0]
	v_pk_mul_f32 v[32:33], v[32:33], v[246:247] op_sel_hi:[1,0]
	v_pk_mul_f32 v[30:31], v[30:31], v[246:247] op_sel_hi:[1,0]
	v_pk_mul_f32 v[28:29], v[28:29], v[246:247] op_sel_hi:[1,0]
	v_pk_mul_f32 v[26:27], v[26:27], v[246:247] op_sel_hi:[1,0]
	v_pk_mul_f32 v[24:25], v[24:25], v[246:247] op_sel_hi:[1,0]
	v_pk_mul_f32 v[22:23], v[22:23], v[246:247] op_sel_hi:[1,0]
	v_pk_mul_f32 v[20:21], v[20:21], v[246:247] op_sel_hi:[1,0]
	v_pk_mul_f32 v[18:19], v[18:19], v[246:247] op_sel_hi:[1,0]
	v_pk_mul_f32 v[16:17], v[16:17], v[246:247] op_sel_hi:[1,0]
	v_mul_f32_e32 v182, v182, v246
.Lattn_pair_nrb:
	v_add_f32_e32 v182, v182, v238
	s_cmp_eq_u32 s11, 0
	s_cbranch_scc0 .Lattn_pair_b6plain
	s_add_i32 s14, s12, 2
	s_cmp_gt_u32 s14, s10
	s_cbranch_scc1 .Lattn_pair_b6plain
	s_and_b32 s14, s13, 1
	s_mul_i32 s15, s14, 0x8800
	s_mul_i32 s14, s14, 0x9000
	v_add3_u32 v246, v176, s15, v174
	v_add3_u32 v247, v177, s14, v175
	s_waitcnt lgkmcnt(6)
	v_mfma_f32_32x32x16_bf16 v[64:79], v[242:245], v[184:187], v[64:79]
	ds_read_b64_tr_b16 v[226:227], v0 offset:20480
	ds_read_b64_tr_b16 v[228:229], v0 offset:22528
	s_waitcnt vmcnt(7)
	ds_write_b128 v246, v[128:131]
	s_waitcnt lgkmcnt(7)
	v_mfma_f32_32x32x16_bf16 v[48:63], v[2:5], v[184:187], v[48:63]
	ds_read_b64_tr_b16 v[230:231], v225 offset:20480
	ds_read_b64_tr_b16 v[232:233], v225 offset:22528
	s_waitcnt vmcnt(6)
	ds_write_b128 v247, v[132:135]
	s_waitcnt lgkmcnt(8)
	v_mfma_f32_32x32x16_bf16 v[32:47], v[8:11], v[184:187], v[32:47]
	ds_read_b64_tr_b16 v[234:235], v6 offset:20480
	ds_read_b64_tr_b16 v[236:237], v6 offset:22528
	s_waitcnt vmcnt(5)
	ds_write_b128 v246, v[136:139] offset:8704
	s_waitcnt lgkmcnt(9)
	v_mfma_f32_32x32x16_bf16 v[16:31], v[12:15], v[184:187], v[16:31]
	ds_read_b64_tr_b16 v[242:243], v248 offset:20480
	ds_read_b64_tr_b16 v[244:245], v248 offset:22528
	s_waitcnt vmcnt(4)
	ds_write_b128 v247, v[140:143] offset:8192
	s_waitcnt lgkmcnt(10)
	v_mfma_f32_32x32x16_bf16 v[64:79], v[226:229], v[192:195], v[64:79]
	ds_read_b64_tr_b16 v[2:3], v0 offset:24576
	ds_read_b64_tr_b16 v[4:5], v0 offset:26624
	s_waitcnt vmcnt(3)
	ds_write_b128 v246, v[144:147] offset:17408
	s_waitcnt lgkmcnt(10)
	v_mfma_f32_32x32x16_bf16 v[48:63], v[230:233], v[192:195], v[48:63]
	ds_read_b64_tr_b16 v[8:9], v225 offset:24576
	ds_read_b64_tr_b16 v[10:11], v225 offset:26624
	s_waitcnt vmcnt(2)
	ds_write_b128 v247, v[148:151] offset:16384
	s_waitcnt lgkmcnt(10)
	v_mfma_f32_32x32x16_bf16 v[32:47], v[234:237], v[192:195], v[32:47]
	ds_read_b64_tr_b16 v[12:13], v6 offset:24576
	ds_read_b64_tr_b16 v[14:15], v6 offset:26624
	s_waitcnt vmcnt(1)
	ds_write_b128 v246, v[152:155] offset:26112
	s_waitcnt lgkmcnt(10)
	v_mfma_f32_32x32x16_bf16 v[16:31], v[242:245], v[192:195], v[16:31]
	ds_read_b64_tr_b16 v[226:227], v248 offset:24576
	ds_read_b64_tr_b16 v[228:229], v248 offset:26624
	s_waitcnt vmcnt(0)
	ds_write_b128 v247, v[156:159] offset:24576
	s_waitcnt lgkmcnt(10)
	v_mfma_f32_32x32x16_bf16 v[64:79], v[2:5], v[200:203], v[64:79]
	ds_read_b64_tr_b16 v[230:231], v0 offset:28672
	ds_read_b64_tr_b16 v[232:233], v0 offset:30720
	v_lshlrev_b32_e32 v84, 1, v173
	v_add_u32_e32 v80, 0xffffffa0, v164
	v_ashrrev_i32_e32 v81, 31, v80
	v_lshlrev_b64 v[82:83], 11, v[80:81]
	v_or_b32_e32 v82, v82, v84
	s_waitcnt lgkmcnt(9)
	v_mfma_f32_32x32x16_bf16 v[48:63], v[8:11], v[200:203], v[48:63]
	ds_read_b64_tr_b16 v[234:235], v225 offset:28672
	ds_read_b64_tr_b16 v[236:237], v225 offset:30720
	v_lshl_add_u64 v[86:87], s[86:87], 0, v[82:83]
	v_lshl_add_u64 v[88:89], s[88:89], 0, v[82:83]
	global_load_dwordx4 v[128:131], v[86:87], off
	global_load_dwordx4 v[132:135], v[88:89], off
	s_waitcnt lgkmcnt(8)
	v_mfma_f32_32x32x16_bf16 v[32:47], v[12:15], v[200:203], v[32:47]
	ds_read_b64_tr_b16 v[242:243], v6 offset:28672
	ds_read_b64_tr_b16 v[244:245], v6 offset:30720
	v_subrev_u32_e32 v80, 64, v164
	v_ashrrev_i32_e32 v81, 31, v80
	v_lshlrev_b64 v[82:83], 11, v[80:81]
	v_or_b32_e32 v82, v82, v84
	s_waitcnt lgkmcnt(7)
	v_mfma_f32_32x32x16_bf16 v[16:31], v[226:229], v[200:203], v[16:31]
	ds_read_b64_tr_b16 v[2:3], v248 offset:28672
	ds_read_b64_tr_b16 v[4:5], v248 offset:30720
	v_lshl_add_u64 v[86:87], s[86:87], 0, v[82:83]
	v_lshl_add_u64 v[88:89], s[88:89], 0, v[82:83]
	global_load_dwordx4 v[136:139], v[86:87], off
	global_load_dwordx4 v[140:143], v[88:89], off
	s_waitcnt lgkmcnt(6)
	v_mfma_f32_32x32x16_bf16 v[64:79], v[230:233], v[208:211], v[64:79]
	v_subrev_u32_e32 v80, 32, v164
	v_ashrrev_i32_e32 v81, 31, v80
	v_lshlrev_b64 v[82:83], 11, v[80:81]
	v_or_b32_e32 v82, v82, v84
	s_waitcnt lgkmcnt(4)
	v_mfma_f32_32x32x16_bf16 v[48:63], v[234:237], v[208:211], v[48:63]
	v_lshl_add_u64 v[86:87], s[86:87], 0, v[82:83]
	v_lshl_add_u64 v[88:89], s[88:89], 0, v[82:83]
	global_load_dwordx4 v[144:147], v[86:87], off
	global_load_dwordx4 v[148:151], v[88:89], off
	s_waitcnt lgkmcnt(2)
	v_mfma_f32_32x32x16_bf16 v[32:47], v[242:245], v[208:211], v[32:47]
	v_ashrrev_i32_e32 v165, 31, v164
	v_lshlrev_b64 v[82:83], 11, v[164:165]
	v_or_b32_e32 v82, v82, v84
	v_lshl_add_u64 v[86:87], s[86:87], 0, v[82:83]
	s_waitcnt lgkmcnt(0)
	v_mfma_f32_32x32x16_bf16 v[16:31], v[2:5], v[208:211], v[16:31]
	v_lshl_add_u64 v[88:89], s[88:89], 0, v[82:83]
	global_load_dwordx4 v[152:155], v[86:87], off
	global_load_dwordx4 v[156:159], v[88:89], off
	s_branch .Lattn_stg_done

.LBB0_125:
	s_cmp_eq_u32 s11, 1
	s_cbranch_scc1 .Lattn_stg_done
	s_cmp_ge_u32 s12, s10
	s_cbranch_scc1 .Lattn_stg_ld
	s_and_b32 s14, s13, 1
	s_mul_i32 s15, s14, 0x8800
	s_mul_i32 s14, s14, 0x9000
	v_add3_u32 v0, v176, s15, v174
	v_add3_u32 v2, v177, s14, v175
	s_waitcnt vmcnt(7)
	ds_write_b128 v0, v[128:131]
	s_waitcnt vmcnt(6)
	ds_write_b128 v2, v[132:135]
	s_waitcnt vmcnt(5)
	ds_write_b128 v0, v[136:139] offset:8704
	s_waitcnt vmcnt(4)
	ds_write_b128 v2, v[140:143] offset:8192
	s_waitcnt vmcnt(3)
	ds_write_b128 v0, v[144:147] offset:17408
	s_waitcnt vmcnt(2)
	ds_write_b128 v2, v[148:151] offset:16384
	s_waitcnt vmcnt(1)
	ds_write_b128 v0, v[152:155] offset:26112
	s_waitcnt vmcnt(0)
	ds_write_b128 v2, v[156:159] offset:24576

.Lattn_stg_done:
	s_add_i32 s2, s2, 2
	s_cmp_eq_u32 s12, s10
	v_add_u32_e32 v164, 0x80, v164
	s_waitcnt lgkmcnt(0)
	s_barrier
	s_cbranch_scc0 .LBB0_112
	s_cmp_eq_u32 s11, 0
	s_cbranch_scc0 .Lattn_skip_b2
	s_barrier
.Lattn_skip_b2:
	v_and_b32_e32 v2, 64, v220
	v_xor_b32_e32 v0, 32, v220
	v_add_u32_e32 v2, 64, v2
	v_cmp_lt_i32_e32 vcc, v0, v2
	s_lshl_b32 s2, s8, 14
	s_add_i32 s2, s2, 0
	v_cndmask_b32_e32 v0, v220, v0, vcc
	s_waitcnt vmcnt(1)
	v_lshlrev_b32_e32 v121, 2, v0
	ds_bpermute_b32 v0, v121, v182
	s_cmp_eq_u32 s11, 1
	v_lshl_add_u32 v2, v170, 2, s2
	s_waitcnt lgkmcnt(0)
	v_add_f32_e32 v0, v182, v0
	s_cbranch_scc0 .LBB0_128
	v_div_scale_f32 v3, s[2:3], v0, v0, v166
	v_rcp_f32_e32 v4, v3
	v_div_scale_f32 v5, vcc, v166, v0, v166
	v_fma_f32 v6, -v3, v4, 1.0
	v_fmac_f32_e32 v4, v6, v4
	v_mul_f32_e32 v6, v5, v4
	v_fma_f32 v7, -v3, v6, v5
	v_fmac_f32_e32 v6, v7, v4
	v_fma_f32 v3, -v3, v6, v5
	v_div_fmas_f32 v3, v3, v4, v6
	v_div_fixup_f32 v3, v3, v0, v166
	v_mul_f32_e32 v4, v64, v3
	v_mul_f32_e32 v5, v65, v3
	ds_write2st64_b32 v2, v4, v5 offset1:1
	v_mul_f32_e32 v4, v66, v3
	v_mul_f32_e32 v5, v67, v3
	ds_write2st64_b32 v2, v4, v5 offset0:2 offset1:3
	v_mul_f32_e32 v4, v68, v3
	v_mul_f32_e32 v5, v69, v3
	ds_write2st64_b32 v2, v4, v5 offset0:4 offset1:5
	v_mul_f32_e32 v4, v70, v3
	v_mul_f32_e32 v5, v71, v3
	ds_write2st64_b32 v2, v4, v5 offset0:6 offset1:7
	v_mul_f32_e32 v4, v72, v3
	v_mul_f32_e32 v5, v73, v3
	ds_write2st64_b32 v2, v4, v5 offset0:8 offset1:9
	v_mul_f32_e32 v4, v74, v3
	v_mul_f32_e32 v5, v75, v3
	ds_write2st64_b32 v2, v4, v5 offset0:10 offset1:11
	v_mul_f32_e32 v4, v76, v3
	v_mul_f32_e32 v5, v77, v3
	ds_write2st64_b32 v2, v4, v5 offset0:12 offset1:13
	v_mul_f32_e32 v4, v78, v3
	v_mul_f32_e32 v5, v79, v3
	ds_write2st64_b32 v2, v4, v5 offset0:14 offset1:15
	v_mul_f32_e32 v4, v48, v3
	v_mul_f32_e32 v5, v49, v3
	ds_write2st64_b32 v2, v4, v5 offset0:16 offset1:17
	v_mul_f32_e32 v4, v50, v3
	v_mul_f32_e32 v5, v51, v3
	ds_write2st64_b32 v2, v4, v5 offset0:18 offset1:19
	v_mul_f32_e32 v4, v52, v3
	v_mul_f32_e32 v5, v53, v3
	ds_write2st64_b32 v2, v4, v5 offset0:20 offset1:21
	v_mul_f32_e32 v4, v54, v3
	v_mul_f32_e32 v5, v55, v3
	ds_write2st64_b32 v2, v4, v5 offset0:22 offset1:23
	v_mul_f32_e32 v4, v56, v3
	v_mul_f32_e32 v5, v57, v3
	ds_write2st64_b32 v2, v4, v5 offset0:24 offset1:25
	v_mul_f32_e32 v4, v58, v3
	v_mul_f32_e32 v5, v59, v3
	ds_write2st64_b32 v2, v4, v5 offset0:26 offset1:27
	v_mul_f32_e32 v4, v60, v3
	v_mul_f32_e32 v5, v61, v3
	ds_write2st64_b32 v2, v4, v5 offset0:28 offset1:29
	v_mul_f32_e32 v4, v62, v3
	v_mul_f32_e32 v5, v63, v3
	ds_write2st64_b32 v2, v4, v5 offset0:30 offset1:31
	v_mul_f32_e32 v4, v32, v3
	v_mul_f32_e32 v5, v33, v3
	ds_write2st64_b32 v2, v4, v5 offset0:32 offset1:33
	v_mul_f32_e32 v4, v34, v3
	v_mul_f32_e32 v5, v35, v3
	ds_write2st64_b32 v2, v4, v5 offset0:34 offset1:35
	v_mul_f32_e32 v4, v36, v3
	v_mul_f32_e32 v5, v37, v3
	ds_write2st64_b32 v2, v4, v5 offset0:36 offset1:37
	v_mul_f32_e32 v4, v38, v3
	v_mul_f32_e32 v5, v39, v3
	ds_write2st64_b32 v2, v4, v5 offset0:38 offset1:39
	v_mul_f32_e32 v4, v40, v3
	v_mul_f32_e32 v5, v41, v3
	ds_write2st64_b32 v2, v4, v5 offset0:40 offset1:41
	v_mul_f32_e32 v4, v42, v3
	v_mul_f32_e32 v5, v43, v3
	ds_write2st64_b32 v2, v4, v5 offset0:42 offset1:43
	v_mul_f32_e32 v4, v44, v3
	v_mul_f32_e32 v5, v45, v3
	ds_write2st64_b32 v2, v4, v5 offset0:44 offset1:45
	v_mul_f32_e32 v4, v46, v3
	v_mul_f32_e32 v5, v47, v3
	ds_write2st64_b32 v2, v4, v5 offset0:46 offset1:47
	v_mul_f32_e32 v4, v16, v3
	v_mul_f32_e32 v5, v17, v3
	ds_write2st64_b32 v2, v4, v5 offset0:48 offset1:49
	v_mul_f32_e32 v4, v18, v3
	v_mul_f32_e32 v5, v19, v3
	ds_write2st64_b32 v2, v4, v5 offset0:50 offset1:51
	v_mul_f32_e32 v4, v20, v3
	v_mul_f32_e32 v5, v21, v3
	ds_write2st64_b32 v2, v4, v5 offset0:52 offset1:53
	v_mul_f32_e32 v4, v22, v3
	v_mul_f32_e32 v5, v23, v3
	ds_write2st64_b32 v2, v4, v5 offset0:54 offset1:55
	v_mul_f32_e32 v4, v24, v3
	v_mul_f32_e32 v5, v25, v3
	ds_write2st64_b32 v2, v4, v5 offset0:56 offset1:57
	v_mul_f32_e32 v4, v26, v3
	v_mul_f32_e32 v5, v27, v3
	ds_write2st64_b32 v2, v4, v5 offset0:58 offset1:59
	v_mul_f32_e32 v4, v28, v3
	v_mul_f32_e32 v5, v29, v3
	ds_write2st64_b32 v2, v4, v5 offset0:60 offset1:61
	v_mul_f32_e32 v4, v30, v3
	v_mul_f32_e32 v3, v31, v3
	ds_write2st64_b32 v2, v4, v3 offset0:62 offset1:63

.LBB0_364:
	s_andn2_b64 vcc, exec, s[0:1]
	s_cbranch_vccnz .LBB0_378
	s_cmp_gt_i32 s57, 6
	s_mov_b64 s[0:1], -1
	s_cbranch_scc0 .LBB0_376
	v_mov_b32_e32 v0, v216
	v_readlane_b32 s0, v252, 37
	s_nop 1
	v_add_u32_e32 v132, s0, v0
	v_cmp_gt_i32_e32 vcc, 0x20000, v132
	s_and_saveexec_b64 s[8:9], vcc
	s_cbranch_execz .LBB0_375
	v_readlane_b32 s0, v254, 36
	v_readlane_b32 s1, v254, 37
	s_mov_b32 s2, s0
	s_mul_i32 s1, s2, 0xc000
	v_readlane_b32 s12, v249, 56
	s_mul_hi_i32 s0, s0, 0xc000
	v_readlane_b32 s13, v249, 57
	s_add_u32 s1, s12, s1
	s_addc_u32 s0, s13, s0
	s_add_u32 s10, s1, 0x2000
	s_addc_u32 s11, s0, 0
	s_mul_i32 s0, s2, 0xc00
	s_ashr_i32 s1, s0, 31
	v_readlane_b32 s14, v249, 58
	s_lshl_b64 s[0:1], s[0:1], 2
	v_readlane_b32 s15, v249, 59
	s_add_u32 s0, s14, s0
	s_addc_u32 s1, s15, s1
	v_readlane_b32 s19, v249, 63
	v_readlane_b32 s26, v250, 6
	s_add_u32 s12, s0, 0x2000
	s_mov_b32 s19, 0x400000
	s_movk_i32 s26, 0x110
	s_addc_u32 s13, s1, 0
	s_mov_b64 s[14:15], 0
	v_readlane_b32 s16, v249, 60
	v_readlane_b32 s17, v249, 61
	v_readlane_b32 s18, v249, 62
	v_readlane_b32 s20, v250, 0
	v_readlane_b32 s21, v250, 1
	v_readlane_b32 s22, v250, 2
	v_readlane_b32 s23, v250, 3
	v_readlane_b32 s24, v250, 4
	v_readlane_b32 s25, v250, 5
	v_readlane_b32 s27, v250, 7
	s_branch .LBB0_369
.LBB0_369:
	v_readlane_b32 s2, v254, 4
	v_readlane_b32 s3, v254, 5
	v_and_b32_e32 v120, 0x1ff, v132
	v_lshrrev_b32_e32 v121, 9, v132
	v_lshlrev_b32_e32 v122, 3, v120
	s_waitcnt lgkmcnt(0)
	global_load_dwordx2 v[110:111], v122, s[10:11]
	v_add_u32_e32 v123, 0x3000, v122
	global_load_dwordx2 v[112:113], v123, s[10:11]
	v_add_u32_e32 v125, 0x6000, v122
	global_load_dwordx2 v[114:115], v125, s[10:11]
	v_add_u32_e32 v126, 0x9000, v122
	global_load_dwordx2 v[116:117], v126, s[10:11]
	global_load_dwordx2 v[118:119], v122, s[12:13]
	v_lshlrev_b32_e32 v124, 2, v120
	v_lshl_add_u32 v124, v121, 17, v124
	v_and_b32_e32 v125, 0x7f, v121
	v_cmp_ne_u32_e64 s[0:1], 0, v125
	v_add_u32_e32 v126, 0xffffe800, v124
	v_add_u32_e32 v127, 0xfffff800, v124
	v_cndmask_b32_e64 v126, v124, v126, s[0:1]
	v_cndmask_b32_e64 v127, v124, v127, s[0:1]
	global_load_dword v2, v126, s[2:3]
	global_load_dword v3, v126, s[2:3] offset:2048
	global_load_dword v4, v127, s[2:3]
	v_mov_b32_e32 v170, v124
	global_load_dword v5, v170, s[2:3]
	global_load_dword v6, v170, s[2:3] offset:2048
	v_add_u32_e32 v171, 0x1000, v124
	global_load_dword v7, v171, s[2:3]
	global_load_dword v8, v171, s[2:3] offset:2048
	v_add_u32_e32 v172, 0x2000, v124
	global_load_dword v9, v172, s[2:3]
	global_load_dword v10, v172, s[2:3] offset:2048
	v_add_u32_e32 v173, 0x3000, v124
	global_load_dword v11, v173, s[2:3]
	global_load_dword v12, v173, s[2:3] offset:2048
	v_add_u32_e32 v174, 0x4000, v124
	global_load_dword v13, v174, s[2:3]
	global_load_dword v14, v174, s[2:3] offset:2048
	v_add_u32_e32 v175, 0x5000, v124
	global_load_dword v15, v175, s[2:3]
	global_load_dword v16, v175, s[2:3] offset:2048
	v_add_u32_e32 v176, 0x6000, v124
	global_load_dword v17, v176, s[2:3]
	global_load_dword v18, v176, s[2:3] offset:2048
	v_add_u32_e32 v177, 0x7000, v124
	global_load_dword v19, v177, s[2:3]
	global_load_dword v20, v177, s[2:3] offset:2048
	v_add_u32_e32 v178, 0x8000, v124
	global_load_dword v21, v178, s[2:3]
	global_load_dword v22, v178, s[2:3] offset:2048
	v_add_u32_e32 v179, 0x9000, v124
	global_load_dword v23, v179, s[2:3]
	global_load_dword v24, v179, s[2:3] offset:2048
	v_add_u32_e32 v180, 0xa000, v124
	global_load_dword v25, v180, s[2:3]
	global_load_dword v26, v180, s[2:3] offset:2048
	v_add_u32_e32 v181, 0xb000, v124
	global_load_dword v27, v181, s[2:3]
	global_load_dword v28, v181, s[2:3] offset:2048
	v_add_u32_e32 v182, 0xc000, v124
	global_load_dword v29, v182, s[2:3]
	global_load_dword v30, v182, s[2:3] offset:2048
	v_add_u32_e32 v183, 0xd000, v124
	global_load_dword v31, v183, s[2:3]
	global_load_dword v32, v183, s[2:3] offset:2048
	v_add_u32_e32 v184, 0xe000, v124
	global_load_dword v33, v184, s[2:3]
	global_load_dword v34, v184, s[2:3] offset:2048
	v_add_u32_e32 v185, 0xf000, v124
	global_load_dword v35, v185, s[2:3]
	global_load_dword v36, v185, s[2:3] offset:2048
	s_waitcnt vmcnt(0)
	v_add_u32_e32 v186, 0x10000, v124
	global_load_dword v37, v186, s[2:3]
	global_load_dword v38, v186, s[2:3] offset:2048
	v_add_u32_e32 v187, 0x11000, v124
	global_load_dword v39, v187, s[2:3]
	global_load_dword v40, v187, s[2:3] offset:2048
	v_add_u32_e32 v188, 0x12000, v124
	global_load_dword v41, v188, s[2:3]
	global_load_dword v42, v188, s[2:3] offset:2048
	v_add_u32_e32 v189, 0x13000, v124
	global_load_dword v43, v189, s[2:3]
	global_load_dword v44, v189, s[2:3] offset:2048
	v_add_u32_e32 v190, 0x14000, v124
	global_load_dword v45, v190, s[2:3]
	global_load_dword v46, v190, s[2:3] offset:2048
	v_add_u32_e32 v191, 0x15000, v124
	global_load_dword v47, v191, s[2:3]
	global_load_dword v48, v191, s[2:3] offset:2048
	v_add_u32_e32 v192, 0x16000, v124
	global_load_dword v49, v192, s[2:3]
	global_load_dword v50, v192, s[2:3] offset:2048
	v_add_u32_e32 v193, 0x17000, v124
	global_load_dword v51, v193, s[2:3]
	global_load_dword v52, v193, s[2:3] offset:2048
	v_add_u32_e32 v194, 0x18000, v124
	global_load_dword v53, v194, s[2:3]
	global_load_dword v54, v194, s[2:3] offset:2048
	v_add_u32_e32 v195, 0x19000, v124
	global_load_dword v55, v195, s[2:3]
	global_load_dword v56, v195, s[2:3] offset:2048
	v_add_u32_e32 v196, 0x1a000, v124
	global_load_dword v57, v196, s[2:3]
	global_load_dword v58, v196, s[2:3] offset:2048
	v_add_u32_e32 v197, 0x1b000, v124
	global_load_dword v59, v197, s[2:3]
	global_load_dword v60, v197, s[2:3] offset:2048
	v_add_u32_e32 v198, 0x1c000, v124
	global_load_dword v61, v198, s[2:3]
	global_load_dword v62, v198, s[2:3] offset:2048
	v_add_u32_e32 v199, 0x1d000, v124
	global_load_dword v63, v199, s[2:3]
	global_load_dword v64, v199, s[2:3] offset:2048
	v_add_u32_e32 v200, 0x1e000, v124
	global_load_dword v65, v200, s[2:3]
	global_load_dword v66, v200, s[2:3] offset:2048
	v_add_u32_e32 v201, 0x1f000, v124
	global_load_dword v67, v201, s[2:3]
	global_load_dword v68, v201, s[2:3] offset:2048
	v_cndmask_b32_e64 v2, 0, v2, s[0:1]
	v_cndmask_b32_e64 v3, 0, v3, s[0:1]
	v_cndmask_b32_e64 v4, 0, v4, s[0:1]
	v_lshlrev_b32_e32 v101, 16, v2
	v_and_b32_e32 v105, 0xffff0000, v2
	v_lshlrev_b32_e32 v102, 16, v3
	v_and_b32_e32 v106, 0xffff0000, v3
	v_lshlrev_b32_e32 v103, 16, v4
	v_and_b32_e32 v107, 0xffff0000, v4
	v_lshlrev_b32_e32 v104, 16, v5
	v_and_b32_e32 v108, 0xffff0000, v5
	v_fma_f32 v120, v110, v101, v118
	v_fma_f32 v121, v111, v105, v119
	v_fmac_f32_e32 v120, v112, v102
	v_fmac_f32_e32 v121, v113, v106
	v_fmac_f32_e32 v120, v114, v103
	v_fmac_f32_e32 v121, v115, v107
	v_fmac_f32_e32 v120, v116, v104
	v_fmac_f32_e32 v121, v117, v108
	v_mul_f32_e32 v122, 0xbfb8aa3b, v120
	v_mul_f32_e32 v123, 0xbfb8aa3b, v121
	v_exp_f32_e32 v122, v122
	v_exp_f32_e32 v123, v123
	s_nop 0
	v_add_f32_e32 v122, 1.0, v122
	v_add_f32_e32 v123, 1.0, v123
	v_rcp_f32_e32 v122, v122
	v_rcp_f32_e32 v123, v123
	s_nop 0
	v_mul_f32_e32 v120, v120, v122
	v_mul_f32_e32 v121, v121, v123
	v_cvt_pk_bf16_f32 v69, v120, v121
	v_lshlrev_b32_e32 v101, 16, v6
	v_and_b32_e32 v105, 0xffff0000, v6
	v_fma_f32 v120, v110, v102, v118
	v_fma_f32 v121, v111, v106, v119
	v_fmac_f32_e32 v120, v112, v103
	v_fmac_f32_e32 v121, v113, v107
	v_fmac_f32_e32 v120, v114, v104
	v_fmac_f32_e32 v121, v115, v108
	v_fmac_f32_e32 v120, v116, v101
	v_fmac_f32_e32 v121, v117, v105
	v_mul_f32_e32 v122, 0xbfb8aa3b, v120
	v_mul_f32_e32 v123, 0xbfb8aa3b, v121
	v_exp_f32_e32 v122, v122
	v_exp_f32_e32 v123, v123
	s_nop 0
	v_add_f32_e32 v122, 1.0, v122
	v_add_f32_e32 v123, 1.0, v123
	v_rcp_f32_e32 v122, v122
	v_rcp_f32_e32 v123, v123
	s_nop 0
	v_mul_f32_e32 v120, v120, v122
	v_mul_f32_e32 v121, v121, v123
	v_cvt_pk_bf16_f32 v70, v120, v121
	v_lshlrev_b32_e32 v102, 16, v7
	v_and_b32_e32 v106, 0xffff0000, v7
	v_fma_f32 v120, v110, v103, v118
	v_fma_f32 v121, v111, v107, v119
	v_fmac_f32_e32 v120, v112, v104
	v_fmac_f32_e32 v121, v113, v108
	v_fmac_f32_e32 v120, v114, v101
	v_fmac_f32_e32 v121, v115, v105
	v_fmac_f32_e32 v120, v116, v102
	v_fmac_f32_e32 v121, v117, v106
	v_mul_f32_e32 v122, 0xbfb8aa3b, v120
	v_mul_f32_e32 v123, 0xbfb8aa3b, v121
	v_exp_f32_e32 v122, v122
	v_exp_f32_e32 v123, v123
	s_nop 0
	v_add_f32_e32 v122, 1.0, v122
	v_add_f32_e32 v123, 1.0, v123
	v_rcp_f32_e32 v122, v122
	v_rcp_f32_e32 v123, v123
	s_nop 0
	v_mul_f32_e32 v120, v120, v122
	v_mul_f32_e32 v121, v121, v123
	v_cvt_pk_bf16_f32 v71, v120, v121
	v_lshlrev_b32_e32 v103, 16, v8
	v_and_b32_e32 v107, 0xffff0000, v8
	v_fma_f32 v120, v110, v104, v118
	v_fma_f32 v121, v111, v108, v119
	v_fmac_f32_e32 v120, v112, v101
	v_fmac_f32_e32 v121, v113, v105
	v_fmac_f32_e32 v120, v114, v102
	v_fmac_f32_e32 v121, v115, v106
	v_fmac_f32_e32 v120, v116, v103
	v_fmac_f32_e32 v121, v117, v107
	v_mul_f32_e32 v122, 0xbfb8aa3b, v120
	v_mul_f32_e32 v123, 0xbfb8aa3b, v121
	v_exp_f32_e32 v122, v122
	v_exp_f32_e32 v123, v123
	s_nop 0
	v_add_f32_e32 v122, 1.0, v122
	v_add_f32_e32 v123, 1.0, v123
	v_rcp_f32_e32 v122, v122
	v_rcp_f32_e32 v123, v123
	s_nop 0
	v_mul_f32_e32 v120, v120, v122
	v_mul_f32_e32 v121, v121, v123
	v_cvt_pk_bf16_f32 v72, v120, v121
	v_lshlrev_b32_e32 v104, 16, v9
	v_and_b32_e32 v108, 0xffff0000, v9
	v_fma_f32 v120, v110, v101, v118
	v_fma_f32 v121, v111, v105, v119
	v_fmac_f32_e32 v120, v112, v102
	v_fmac_f32_e32 v121, v113, v106
	v_fmac_f32_e32 v120, v114, v103
	v_fmac_f32_e32 v121, v115, v107
	v_fmac_f32_e32 v120, v116, v104
	v_fmac_f32_e32 v121, v117, v108
	v_mul_f32_e32 v122, 0xbfb8aa3b, v120
	v_mul_f32_e32 v123, 0xbfb8aa3b, v121
	v_exp_f32_e32 v122, v122
	v_exp_f32_e32 v123, v123
	s_nop 0
	v_add_f32_e32 v122, 1.0, v122
	v_add_f32_e32 v123, 1.0, v123
	v_rcp_f32_e32 v122, v122
	v_rcp_f32_e32 v123, v123
	s_nop 0
	v_mul_f32_e32 v120, v120, v122
	v_mul_f32_e32 v121, v121, v123
	v_cvt_pk_bf16_f32 v73, v120, v121
	v_lshlrev_b32_e32 v101, 16, v10
	v_and_b32_e32 v105, 0xffff0000, v10
	v_fma_f32 v120, v110, v102, v118
	v_fma_f32 v121, v111, v106, v119
	v_fmac_f32_e32 v120, v112, v103
	v_fmac_f32_e32 v121, v113, v107
	v_fmac_f32_e32 v120, v114, v104
	v_fmac_f32_e32 v121, v115, v108
	v_fmac_f32_e32 v120, v116, v101
	v_fmac_f32_e32 v121, v117, v105
	v_mul_f32_e32 v122, 0xbfb8aa3b, v120
	v_mul_f32_e32 v123, 0xbfb8aa3b, v121
	v_exp_f32_e32 v122, v122
	v_exp_f32_e32 v123, v123
	s_nop 0
	v_add_f32_e32 v122, 1.0, v122
	v_add_f32_e32 v123, 1.0, v123
	v_rcp_f32_e32 v122, v122
	v_rcp_f32_e32 v123, v123
	s_nop 0
	v_mul_f32_e32 v120, v120, v122
	v_mul_f32_e32 v121, v121, v123
	v_cvt_pk_bf16_f32 v74, v120, v121
	v_lshlrev_b32_e32 v102, 16, v11
	v_and_b32_e32 v106, 0xffff0000, v11
	v_fma_f32 v120, v110, v103, v118
	v_fma_f32 v121, v111, v107, v119
	v_fmac_f32_e32 v120, v112, v104
	v_fmac_f32_e32 v121, v113, v108
	v_fmac_f32_e32 v120, v114, v101
	v_fmac_f32_e32 v121, v115, v105
	v_fmac_f32_e32 v120, v116, v102
	v_fmac_f32_e32 v121, v117, v106
	v_mul_f32_e32 v122, 0xbfb8aa3b, v120
	v_mul_f32_e32 v123, 0xbfb8aa3b, v121
	v_exp_f32_e32 v122, v122
	v_exp_f32_e32 v123, v123
	s_nop 0
	v_add_f32_e32 v122, 1.0, v122
	v_add_f32_e32 v123, 1.0, v123
	v_rcp_f32_e32 v122, v122
	v_rcp_f32_e32 v123, v123
	s_nop 0
	v_mul_f32_e32 v120, v120, v122
	v_mul_f32_e32 v121, v121, v123
	v_cvt_pk_bf16_f32 v75, v120, v121
	v_lshlrev_b32_e32 v103, 16, v12
	v_and_b32_e32 v107, 0xffff0000, v12
	v_fma_f32 v120, v110, v104, v118
	v_fma_f32 v121, v111, v108, v119
	v_fmac_f32_e32 v120, v112, v101
	v_fmac_f32_e32 v121, v113, v105
	v_fmac_f32_e32 v120, v114, v102
	v_fmac_f32_e32 v121, v115, v106
	v_fmac_f32_e32 v120, v116, v103
	v_fmac_f32_e32 v121, v117, v107
	v_mul_f32_e32 v122, 0xbfb8aa3b, v120
	v_mul_f32_e32 v123, 0xbfb8aa3b, v121
	v_exp_f32_e32 v122, v122
	v_exp_f32_e32 v123, v123
	s_nop 0
	v_add_f32_e32 v122, 1.0, v122
	v_add_f32_e32 v123, 1.0, v123
	v_rcp_f32_e32 v122, v122
	v_rcp_f32_e32 v123, v123
	s_nop 0
	v_mul_f32_e32 v120, v120, v122
	v_mul_f32_e32 v121, v121, v123
	v_cvt_pk_bf16_f32 v76, v120, v121
	v_lshlrev_b32_e32 v104, 16, v13
	v_and_b32_e32 v108, 0xffff0000, v13
	v_fma_f32 v120, v110, v101, v118
	v_fma_f32 v121, v111, v105, v119
	v_fmac_f32_e32 v120, v112, v102
	v_fmac_f32_e32 v121, v113, v106
	v_fmac_f32_e32 v120, v114, v103
	v_fmac_f32_e32 v121, v115, v107
	v_fmac_f32_e32 v120, v116, v104
	v_fmac_f32_e32 v121, v117, v108
	v_mul_f32_e32 v122, 0xbfb8aa3b, v120
	v_mul_f32_e32 v123, 0xbfb8aa3b, v121
	v_exp_f32_e32 v122, v122
	v_exp_f32_e32 v123, v123
	s_nop 0
	v_add_f32_e32 v122, 1.0, v122
	v_add_f32_e32 v123, 1.0, v123
	v_rcp_f32_e32 v122, v122
	v_rcp_f32_e32 v123, v123
	s_nop 0
	v_mul_f32_e32 v120, v120, v122
	v_mul_f32_e32 v121, v121, v123
	v_cvt_pk_bf16_f32 v77, v120, v121
	v_lshlrev_b32_e32 v101, 16, v14
	v_and_b32_e32 v105, 0xffff0000, v14
	v_fma_f32 v120, v110, v102, v118
	v_fma_f32 v121, v111, v106, v119
	v_fmac_f32_e32 v120, v112, v103
	v_fmac_f32_e32 v121, v113, v107
	v_fmac_f32_e32 v120, v114, v104
	v_fmac_f32_e32 v121, v115, v108
	v_fmac_f32_e32 v120, v116, v101
	v_fmac_f32_e32 v121, v117, v105
	v_mul_f32_e32 v122, 0xbfb8aa3b, v120
	v_mul_f32_e32 v123, 0xbfb8aa3b, v121
	v_exp_f32_e32 v122, v122
	v_exp_f32_e32 v123, v123
	s_nop 0
	v_add_f32_e32 v122, 1.0, v122
	v_add_f32_e32 v123, 1.0, v123
	v_rcp_f32_e32 v122, v122
	v_rcp_f32_e32 v123, v123
	s_nop 0
	v_mul_f32_e32 v120, v120, v122
	v_mul_f32_e32 v121, v121, v123
	v_cvt_pk_bf16_f32 v78, v120, v121
	v_lshlrev_b32_e32 v102, 16, v15
	v_and_b32_e32 v106, 0xffff0000, v15
	v_fma_f32 v120, v110, v103, v118
	v_fma_f32 v121, v111, v107, v119
	v_fmac_f32_e32 v120, v112, v104
	v_fmac_f32_e32 v121, v113, v108
	v_fmac_f32_e32 v120, v114, v101
	v_fmac_f32_e32 v121, v115, v105
	v_fmac_f32_e32 v120, v116, v102
	v_fmac_f32_e32 v121, v117, v106
	v_mul_f32_e32 v122, 0xbfb8aa3b, v120
	v_mul_f32_e32 v123, 0xbfb8aa3b, v121
	v_exp_f32_e32 v122, v122
	v_exp_f32_e32 v123, v123
	s_nop 0
	v_add_f32_e32 v122, 1.0, v122
	v_add_f32_e32 v123, 1.0, v123
	v_rcp_f32_e32 v122, v122
	v_rcp_f32_e32 v123, v123
	s_nop 0
	v_mul_f32_e32 v120, v120, v122
	v_mul_f32_e32 v121, v121, v123
	v_cvt_pk_bf16_f32 v79, v120, v121
	v_lshlrev_b32_e32 v103, 16, v16
	v_and_b32_e32 v107, 0xffff0000, v16
	v_fma_f32 v120, v110, v104, v118
	v_fma_f32 v121, v111, v108, v119
	v_fmac_f32_e32 v120, v112, v101
	v_fmac_f32_e32 v121, v113, v105
	v_fmac_f32_e32 v120, v114, v102
	v_fmac_f32_e32 v121, v115, v106
	v_fmac_f32_e32 v120, v116, v103
	v_fmac_f32_e32 v121, v117, v107
	v_mul_f32_e32 v122, 0xbfb8aa3b, v120
	v_mul_f32_e32 v123, 0xbfb8aa3b, v121
	v_exp_f32_e32 v122, v122
	v_exp_f32_e32 v123, v123
	s_nop 0
	v_add_f32_e32 v122, 1.0, v122
	v_add_f32_e32 v123, 1.0, v123
	v_rcp_f32_e32 v122, v122
	v_rcp_f32_e32 v123, v123
	s_nop 0
	v_mul_f32_e32 v120, v120, v122
	v_mul_f32_e32 v121, v121, v123
	v_cvt_pk_bf16_f32 v80, v120, v121
	v_lshlrev_b32_e32 v104, 16, v17
	v_and_b32_e32 v108, 0xffff0000, v17
	v_fma_f32 v120, v110, v101, v118
	v_fma_f32 v121, v111, v105, v119
	v_fmac_f32_e32 v120, v112, v102
	v_fmac_f32_e32 v121, v113, v106
	v_fmac_f32_e32 v120, v114, v103
	v_fmac_f32_e32 v121, v115, v107
	v_fmac_f32_e32 v120, v116, v104
	v_fmac_f32_e32 v121, v117, v108
	v_mul_f32_e32 v122, 0xbfb8aa3b, v120
	v_mul_f32_e32 v123, 0xbfb8aa3b, v121
	v_exp_f32_e32 v122, v122
	v_exp_f32_e32 v123, v123
	s_nop 0
	v_add_f32_e32 v122, 1.0, v122
	v_add_f32_e32 v123, 1.0, v123
	v_rcp_f32_e32 v122, v122
	v_rcp_f32_e32 v123, v123
	s_nop 0
	v_mul_f32_e32 v120, v120, v122
	v_mul_f32_e32 v121, v121, v123
	v_cvt_pk_bf16_f32 v81, v120, v121
	v_lshlrev_b32_e32 v101, 16, v18
	v_and_b32_e32 v105, 0xffff0000, v18
	v_fma_f32 v120, v110, v102, v118
	v_fma_f32 v121, v111, v106, v119
	v_fmac_f32_e32 v120, v112, v103
	v_fmac_f32_e32 v121, v113, v107
	v_fmac_f32_e32 v120, v114, v104
	v_fmac_f32_e32 v121, v115, v108
	v_fmac_f32_e32 v120, v116, v101
	v_fmac_f32_e32 v121, v117, v105
	v_mul_f32_e32 v122, 0xbfb8aa3b, v120
	v_mul_f32_e32 v123, 0xbfb8aa3b, v121
	v_exp_f32_e32 v122, v122
	v_exp_f32_e32 v123, v123
	s_nop 0
	v_add_f32_e32 v122, 1.0, v122
	v_add_f32_e32 v123, 1.0, v123
	v_rcp_f32_e32 v122, v122
	v_rcp_f32_e32 v123, v123
	s_nop 0
	v_mul_f32_e32 v120, v120, v122
	v_mul_f32_e32 v121, v121, v123
	v_cvt_pk_bf16_f32 v82, v120, v121
	v_lshlrev_b32_e32 v102, 16, v19
	v_and_b32_e32 v106, 0xffff0000, v19
	v_fma_f32 v120, v110, v103, v118
	v_fma_f32 v121, v111, v107, v119
	v_fmac_f32_e32 v120, v112, v104
	v_fmac_f32_e32 v121, v113, v108
	v_fmac_f32_e32 v120, v114, v101
	v_fmac_f32_e32 v121, v115, v105
	v_fmac_f32_e32 v120, v116, v102
	v_fmac_f32_e32 v121, v117, v106
	v_mul_f32_e32 v122, 0xbfb8aa3b, v120
	v_mul_f32_e32 v123, 0xbfb8aa3b, v121
	v_exp_f32_e32 v122, v122
	v_exp_f32_e32 v123, v123
	s_nop 0
	v_add_f32_e32 v122, 1.0, v122
	v_add_f32_e32 v123, 1.0, v123
	v_rcp_f32_e32 v122, v122
	v_rcp_f32_e32 v123, v123
	s_nop 0
	v_mul_f32_e32 v120, v120, v122
	v_mul_f32_e32 v121, v121, v123
	v_cvt_pk_bf16_f32 v83, v120, v121
	v_lshlrev_b32_e32 v103, 16, v20
	v_and_b32_e32 v107, 0xffff0000, v20
	v_fma_f32 v120, v110, v104, v118
	v_fma_f32 v121, v111, v108, v119
	v_fmac_f32_e32 v120, v112, v101
	v_fmac_f32_e32 v121, v113, v105
	v_fmac_f32_e32 v120, v114, v102
	v_fmac_f32_e32 v121, v115, v106
	v_fmac_f32_e32 v120, v116, v103
	v_fmac_f32_e32 v121, v117, v107
	v_mul_f32_e32 v122, 0xbfb8aa3b, v120
	v_mul_f32_e32 v123, 0xbfb8aa3b, v121
	v_exp_f32_e32 v122, v122
	v_exp_f32_e32 v123, v123
	s_nop 0
	v_add_f32_e32 v122, 1.0, v122
	v_add_f32_e32 v123, 1.0, v123
	v_rcp_f32_e32 v122, v122
	v_rcp_f32_e32 v123, v123
	s_nop 0
	v_mul_f32_e32 v120, v120, v122
	v_mul_f32_e32 v121, v121, v123
	v_cvt_pk_bf16_f32 v84, v120, v121
	v_lshlrev_b32_e32 v104, 16, v21
	v_and_b32_e32 v108, 0xffff0000, v21
	v_fma_f32 v120, v110, v101, v118
	v_fma_f32 v121, v111, v105, v119
	v_fmac_f32_e32 v120, v112, v102
	v_fmac_f32_e32 v121, v113, v106
	v_fmac_f32_e32 v120, v114, v103
	v_fmac_f32_e32 v121, v115, v107
	v_fmac_f32_e32 v120, v116, v104
	v_fmac_f32_e32 v121, v117, v108
	v_mul_f32_e32 v122, 0xbfb8aa3b, v120
	v_mul_f32_e32 v123, 0xbfb8aa3b, v121
	v_exp_f32_e32 v122, v122
	v_exp_f32_e32 v123, v123
	s_nop 0
	v_add_f32_e32 v122, 1.0, v122
	v_add_f32_e32 v123, 1.0, v123
	v_rcp_f32_e32 v122, v122
	v_rcp_f32_e32 v123, v123
	s_nop 0
	v_mul_f32_e32 v120, v120, v122
	v_mul_f32_e32 v121, v121, v123
	v_cvt_pk_bf16_f32 v85, v120, v121
	v_lshlrev_b32_e32 v101, 16, v22
	v_and_b32_e32 v105, 0xffff0000, v22
	v_fma_f32 v120, v110, v102, v118
	v_fma_f32 v121, v111, v106, v119
	v_fmac_f32_e32 v120, v112, v103
	v_fmac_f32_e32 v121, v113, v107
	v_fmac_f32_e32 v120, v114, v104
	v_fmac_f32_e32 v121, v115, v108
	v_fmac_f32_e32 v120, v116, v101
	v_fmac_f32_e32 v121, v117, v105
	v_mul_f32_e32 v122, 0xbfb8aa3b, v120
	v_mul_f32_e32 v123, 0xbfb8aa3b, v121
	v_exp_f32_e32 v122, v122
	v_exp_f32_e32 v123, v123
	s_nop 0
	v_add_f32_e32 v122, 1.0, v122
	v_add_f32_e32 v123, 1.0, v123
	v_rcp_f32_e32 v122, v122
	v_rcp_f32_e32 v123, v123
	s_nop 0
	v_mul_f32_e32 v120, v120, v122
	v_mul_f32_e32 v121, v121, v123
	v_cvt_pk_bf16_f32 v86, v120, v121
	v_lshlrev_b32_e32 v102, 16, v23
	v_and_b32_e32 v106, 0xffff0000, v23
	v_fma_f32 v120, v110, v103, v118
	v_fma_f32 v121, v111, v107, v119
	v_fmac_f32_e32 v120, v112, v104
	v_fmac_f32_e32 v121, v113, v108
	v_fmac_f32_e32 v120, v114, v101
	v_fmac_f32_e32 v121, v115, v105
	v_fmac_f32_e32 v120, v116, v102
	v_fmac_f32_e32 v121, v117, v106
	v_mul_f32_e32 v122, 0xbfb8aa3b, v120
	v_mul_f32_e32 v123, 0xbfb8aa3b, v121
	v_exp_f32_e32 v122, v122
	v_exp_f32_e32 v123, v123
	s_nop 0
	v_add_f32_e32 v122, 1.0, v122
	v_add_f32_e32 v123, 1.0, v123
	v_rcp_f32_e32 v122, v122
	v_rcp_f32_e32 v123, v123
	s_nop 0
	v_mul_f32_e32 v120, v120, v122
	v_mul_f32_e32 v121, v121, v123
	v_cvt_pk_bf16_f32 v87, v120, v121
	v_lshlrev_b32_e32 v103, 16, v24
	v_and_b32_e32 v107, 0xffff0000, v24
	v_fma_f32 v120, v110, v104, v118
	v_fma_f32 v121, v111, v108, v119
	v_fmac_f32_e32 v120, v112, v101
	v_fmac_f32_e32 v121, v113, v105
	v_fmac_f32_e32 v120, v114, v102
	v_fmac_f32_e32 v121, v115, v106
	v_fmac_f32_e32 v120, v116, v103
	v_fmac_f32_e32 v121, v117, v107
	v_mul_f32_e32 v122, 0xbfb8aa3b, v120
	v_mul_f32_e32 v123, 0xbfb8aa3b, v121
	v_exp_f32_e32 v122, v122
	v_exp_f32_e32 v123, v123
	s_nop 0
	v_add_f32_e32 v122, 1.0, v122
	v_add_f32_e32 v123, 1.0, v123
	v_rcp_f32_e32 v122, v122
	v_rcp_f32_e32 v123, v123
	s_nop 0
	v_mul_f32_e32 v120, v120, v122
	v_mul_f32_e32 v121, v121, v123
	v_cvt_pk_bf16_f32 v88, v120, v121
	v_lshlrev_b32_e32 v104, 16, v25
	v_and_b32_e32 v108, 0xffff0000, v25
	v_fma_f32 v120, v110, v101, v118
	v_fma_f32 v121, v111, v105, v119
	v_fmac_f32_e32 v120, v112, v102
	v_fmac_f32_e32 v121, v113, v106
	v_fmac_f32_e32 v120, v114, v103
	v_fmac_f32_e32 v121, v115, v107
	v_fmac_f32_e32 v120, v116, v104
	v_fmac_f32_e32 v121, v117, v108
	v_mul_f32_e32 v122, 0xbfb8aa3b, v120
	v_mul_f32_e32 v123, 0xbfb8aa3b, v121
	v_exp_f32_e32 v122, v122
	v_exp_f32_e32 v123, v123
	s_nop 0
	v_add_f32_e32 v122, 1.0, v122
	v_add_f32_e32 v123, 1.0, v123
	v_rcp_f32_e32 v122, v122
	v_rcp_f32_e32 v123, v123
	s_nop 0
	v_mul_f32_e32 v120, v120, v122
	v_mul_f32_e32 v121, v121, v123
	v_cvt_pk_bf16_f32 v89, v120, v121
	v_lshlrev_b32_e32 v101, 16, v26
	v_and_b32_e32 v105, 0xffff0000, v26
	v_fma_f32 v120, v110, v102, v118
	v_fma_f32 v121, v111, v106, v119
	v_fmac_f32_e32 v120, v112, v103
	v_fmac_f32_e32 v121, v113, v107
	v_fmac_f32_e32 v120, v114, v104
	v_fmac_f32_e32 v121, v115, v108
	v_fmac_f32_e32 v120, v116, v101
	v_fmac_f32_e32 v121, v117, v105
	v_mul_f32_e32 v122, 0xbfb8aa3b, v120
	v_mul_f32_e32 v123, 0xbfb8aa3b, v121
	v_exp_f32_e32 v122, v122
	v_exp_f32_e32 v123, v123
	s_nop 0
	v_add_f32_e32 v122, 1.0, v122
	v_add_f32_e32 v123, 1.0, v123
	v_rcp_f32_e32 v122, v122
	v_rcp_f32_e32 v123, v123
	s_nop 0
	v_mul_f32_e32 v120, v120, v122
	v_mul_f32_e32 v121, v121, v123
	v_cvt_pk_bf16_f32 v90, v120, v121
	v_lshlrev_b32_e32 v102, 16, v27
	v_and_b32_e32 v106, 0xffff0000, v27
	v_fma_f32 v120, v110, v103, v118
	v_fma_f32 v121, v111, v107, v119
	v_fmac_f32_e32 v120, v112, v104
	v_fmac_f32_e32 v121, v113, v108
	v_fmac_f32_e32 v120, v114, v101
	v_fmac_f32_e32 v121, v115, v105
	v_fmac_f32_e32 v120, v116, v102
	v_fmac_f32_e32 v121, v117, v106
	v_mul_f32_e32 v122, 0xbfb8aa3b, v120
	v_mul_f32_e32 v123, 0xbfb8aa3b, v121
	v_exp_f32_e32 v122, v122
	v_exp_f32_e32 v123, v123
	s_nop 0
	v_add_f32_e32 v122, 1.0, v122
	v_add_f32_e32 v123, 1.0, v123
	v_rcp_f32_e32 v122, v122
	v_rcp_f32_e32 v123, v123
	s_nop 0
	v_mul_f32_e32 v120, v120, v122
	v_mul_f32_e32 v121, v121, v123
	v_cvt_pk_bf16_f32 v91, v120, v121
	v_lshlrev_b32_e32 v103, 16, v28
	v_and_b32_e32 v107, 0xffff0000, v28
	v_fma_f32 v120, v110, v104, v118
	v_fma_f32 v121, v111, v108, v119
	v_fmac_f32_e32 v120, v112, v101
	v_fmac_f32_e32 v121, v113, v105
	v_fmac_f32_e32 v120, v114, v102
	v_fmac_f32_e32 v121, v115, v106
	v_fmac_f32_e32 v120, v116, v103
	v_fmac_f32_e32 v121, v117, v107
	v_mul_f32_e32 v122, 0xbfb8aa3b, v120
	v_mul_f32_e32 v123, 0xbfb8aa3b, v121
	v_exp_f32_e32 v122, v122
	v_exp_f32_e32 v123, v123
	s_nop 0
	v_add_f32_e32 v122, 1.0, v122
	v_add_f32_e32 v123, 1.0, v123
	v_rcp_f32_e32 v122, v122
	v_rcp_f32_e32 v123, v123
	s_nop 0
	v_mul_f32_e32 v120, v120, v122
	v_mul_f32_e32 v121, v121, v123
	v_cvt_pk_bf16_f32 v92, v120, v121
	v_lshlrev_b32_e32 v104, 16, v29
	v_and_b32_e32 v108, 0xffff0000, v29
	v_fma_f32 v120, v110, v101, v118
	v_fma_f32 v121, v111, v105, v119
	v_fmac_f32_e32 v120, v112, v102
	v_fmac_f32_e32 v121, v113, v106
	v_fmac_f32_e32 v120, v114, v103
	v_fmac_f32_e32 v121, v115, v107
	v_fmac_f32_e32 v120, v116, v104
	v_fmac_f32_e32 v121, v117, v108
	v_mul_f32_e32 v122, 0xbfb8aa3b, v120
	v_mul_f32_e32 v123, 0xbfb8aa3b, v121
	v_exp_f32_e32 v122, v122
	v_exp_f32_e32 v123, v123
	s_nop 0
	v_add_f32_e32 v122, 1.0, v122
	v_add_f32_e32 v123, 1.0, v123
	v_rcp_f32_e32 v122, v122
	v_rcp_f32_e32 v123, v123
	s_nop 0
	v_mul_f32_e32 v120, v120, v122
	v_mul_f32_e32 v121, v121, v123
	v_cvt_pk_bf16_f32 v93, v120, v121
	v_lshlrev_b32_e32 v101, 16, v30
	v_and_b32_e32 v105, 0xffff0000, v30
	v_fma_f32 v120, v110, v102, v118
	v_fma_f32 v121, v111, v106, v119
	v_fmac_f32_e32 v120, v112, v103
	v_fmac_f32_e32 v121, v113, v107
	v_fmac_f32_e32 v120, v114, v104
	v_fmac_f32_e32 v121, v115, v108
	v_fmac_f32_e32 v120, v116, v101
	v_fmac_f32_e32 v121, v117, v105
	v_mul_f32_e32 v122, 0xbfb8aa3b, v120
	v_mul_f32_e32 v123, 0xbfb8aa3b, v121
	v_exp_f32_e32 v122, v122
	v_exp_f32_e32 v123, v123
	s_nop 0
	v_add_f32_e32 v122, 1.0, v122
	v_add_f32_e32 v123, 1.0, v123
	v_rcp_f32_e32 v122, v122
	v_rcp_f32_e32 v123, v123
	s_nop 0
	v_mul_f32_e32 v120, v120, v122
	v_mul_f32_e32 v121, v121, v123
	v_cvt_pk_bf16_f32 v94, v120, v121
	v_lshlrev_b32_e32 v102, 16, v31
	v_and_b32_e32 v106, 0xffff0000, v31
	v_fma_f32 v120, v110, v103, v118
	v_fma_f32 v121, v111, v107, v119
	v_fmac_f32_e32 v120, v112, v104
	v_fmac_f32_e32 v121, v113, v108
	v_fmac_f32_e32 v120, v114, v101
	v_fmac_f32_e32 v121, v115, v105
	v_fmac_f32_e32 v120, v116, v102
	v_fmac_f32_e32 v121, v117, v106
	v_mul_f32_e32 v122, 0xbfb8aa3b, v120
	v_mul_f32_e32 v123, 0xbfb8aa3b, v121
	v_exp_f32_e32 v122, v122
	v_exp_f32_e32 v123, v123
	s_nop 0
	v_add_f32_e32 v122, 1.0, v122
	v_add_f32_e32 v123, 1.0, v123
	v_rcp_f32_e32 v122, v122
	v_rcp_f32_e32 v123, v123
	s_nop 0
	v_mul_f32_e32 v120, v120, v122
	v_mul_f32_e32 v121, v121, v123
	v_cvt_pk_bf16_f32 v95, v120, v121
	v_lshlrev_b32_e32 v103, 16, v32
	v_and_b32_e32 v107, 0xffff0000, v32
	v_fma_f32 v120, v110, v104, v118
	v_fma_f32 v121, v111, v108, v119
	v_fmac_f32_e32 v120, v112, v101
	v_fmac_f32_e32 v121, v113, v105
	v_fmac_f32_e32 v120, v114, v102
	v_fmac_f32_e32 v121, v115, v106
	v_fmac_f32_e32 v120, v116, v103
	v_fmac_f32_e32 v121, v117, v107
	v_mul_f32_e32 v122, 0xbfb8aa3b, v120
	v_mul_f32_e32 v123, 0xbfb8aa3b, v121
	v_exp_f32_e32 v122, v122
	v_exp_f32_e32 v123, v123
	s_nop 0
	v_add_f32_e32 v122, 1.0, v122
	v_add_f32_e32 v123, 1.0, v123
	v_rcp_f32_e32 v122, v122
	v_rcp_f32_e32 v123, v123
	s_nop 0
	v_mul_f32_e32 v120, v120, v122
	v_mul_f32_e32 v121, v121, v123
	v_cvt_pk_bf16_f32 v96, v120, v121
	v_lshlrev_b32_e32 v104, 16, v33
	v_and_b32_e32 v108, 0xffff0000, v33
	v_fma_f32 v120, v110, v101, v118
	v_fma_f32 v121, v111, v105, v119
	v_fmac_f32_e32 v120, v112, v102
	v_fmac_f32_e32 v121, v113, v106
	v_fmac_f32_e32 v120, v114, v103
	v_fmac_f32_e32 v121, v115, v107
	v_fmac_f32_e32 v120, v116, v104
	v_fmac_f32_e32 v121, v117, v108
	v_mul_f32_e32 v122, 0xbfb8aa3b, v120
	v_mul_f32_e32 v123, 0xbfb8aa3b, v121
	v_exp_f32_e32 v122, v122
	v_exp_f32_e32 v123, v123
	s_nop 0
	v_add_f32_e32 v122, 1.0, v122
	v_add_f32_e32 v123, 1.0, v123
	v_rcp_f32_e32 v122, v122
	v_rcp_f32_e32 v123, v123
	s_nop 0
	v_mul_f32_e32 v120, v120, v122
	v_mul_f32_e32 v121, v121, v123
	v_cvt_pk_bf16_f32 v97, v120, v121
	v_lshlrev_b32_e32 v101, 16, v34
	v_and_b32_e32 v105, 0xffff0000, v34
	v_fma_f32 v120, v110, v102, v118
	v_fma_f32 v121, v111, v106, v119
	v_fmac_f32_e32 v120, v112, v103
	v_fmac_f32_e32 v121, v113, v107
	v_fmac_f32_e32 v120, v114, v104
	v_fmac_f32_e32 v121, v115, v108
	v_fmac_f32_e32 v120, v116, v101
	v_fmac_f32_e32 v121, v117, v105
	v_mul_f32_e32 v122, 0xbfb8aa3b, v120
	v_mul_f32_e32 v123, 0xbfb8aa3b, v121
	v_exp_f32_e32 v122, v122
	v_exp_f32_e32 v123, v123
	s_nop 0
	v_add_f32_e32 v122, 1.0, v122
	v_add_f32_e32 v123, 1.0, v123
	v_rcp_f32_e32 v122, v122
	v_rcp_f32_e32 v123, v123
	s_nop 0
	v_mul_f32_e32 v120, v120, v122
	v_mul_f32_e32 v121, v121, v123
	v_cvt_pk_bf16_f32 v98, v120, v121
	v_lshlrev_b32_e32 v102, 16, v35
	v_and_b32_e32 v106, 0xffff0000, v35
	v_fma_f32 v120, v110, v103, v118
	v_fma_f32 v121, v111, v107, v119
	v_fmac_f32_e32 v120, v112, v104
	v_fmac_f32_e32 v121, v113, v108
	v_fmac_f32_e32 v120, v114, v101
	v_fmac_f32_e32 v121, v115, v105
	v_fmac_f32_e32 v120, v116, v102
	v_fmac_f32_e32 v121, v117, v106
	v_mul_f32_e32 v122, 0xbfb8aa3b, v120
	v_mul_f32_e32 v123, 0xbfb8aa3b, v121
	v_exp_f32_e32 v122, v122
	v_exp_f32_e32 v123, v123
	s_nop 0
	v_add_f32_e32 v122, 1.0, v122
	v_add_f32_e32 v123, 1.0, v123
	v_rcp_f32_e32 v122, v122
	v_rcp_f32_e32 v123, v123
	s_nop 0
	v_mul_f32_e32 v120, v120, v122
	v_mul_f32_e32 v121, v121, v123
	v_cvt_pk_bf16_f32 v99, v120, v121
	v_lshlrev_b32_e32 v103, 16, v36
	v_and_b32_e32 v107, 0xffff0000, v36
	v_fma_f32 v120, v110, v104, v118
	v_fma_f32 v121, v111, v108, v119
	v_fmac_f32_e32 v120, v112, v101
	v_fmac_f32_e32 v121, v113, v105
	v_fmac_f32_e32 v120, v114, v102
	v_fmac_f32_e32 v121, v115, v106
	v_fmac_f32_e32 v120, v116, v103
	v_fmac_f32_e32 v121, v117, v107
	v_mul_f32_e32 v122, 0xbfb8aa3b, v120
	v_mul_f32_e32 v123, 0xbfb8aa3b, v121
	v_exp_f32_e32 v122, v122
	v_exp_f32_e32 v123, v123
	s_nop 0
	v_add_f32_e32 v122, 1.0, v122
	v_add_f32_e32 v123, 1.0, v123
	v_rcp_f32_e32 v122, v122
	v_rcp_f32_e32 v123, v123
	s_nop 0
	v_mul_f32_e32 v120, v120, v122
	v_mul_f32_e32 v121, v121, v123
	v_cvt_pk_bf16_f32 v100, v120, v121
	s_waitcnt vmcnt(0)
	global_store_dword v170, v69, s[60:61]
	global_store_dword v170, v70, s[60:61] offset:2048
	global_store_dword v171, v71, s[60:61]
	global_store_dword v171, v72, s[60:61] offset:2048
	global_store_dword v172, v73, s[60:61]
	global_store_dword v172, v74, s[60:61] offset:2048
	global_store_dword v173, v75, s[60:61]
	global_store_dword v173, v76, s[60:61] offset:2048
	global_store_dword v174, v77, s[60:61]
	global_store_dword v174, v78, s[60:61] offset:2048
	global_store_dword v175, v79, s[60:61]
	global_store_dword v175, v80, s[60:61] offset:2048
	global_store_dword v176, v81, s[60:61]
	global_store_dword v176, v82, s[60:61] offset:2048
	global_store_dword v177, v83, s[60:61]
	global_store_dword v177, v84, s[60:61] offset:2048
	global_store_dword v178, v85, s[60:61]
	global_store_dword v178, v86, s[60:61] offset:2048
	global_store_dword v179, v87, s[60:61]
	global_store_dword v179, v88, s[60:61] offset:2048
	global_store_dword v180, v89, s[60:61]
	global_store_dword v180, v90, s[60:61] offset:2048
	global_store_dword v181, v91, s[60:61]
	global_store_dword v181, v92, s[60:61] offset:2048
	global_store_dword v182, v93, s[60:61]
	global_store_dword v182, v94, s[60:61] offset:2048
	global_store_dword v183, v95, s[60:61]
	global_store_dword v183, v96, s[60:61] offset:2048
	global_store_dword v184, v97, s[60:61]
	global_store_dword v184, v98, s[60:61] offset:2048
	global_store_dword v185, v99, s[60:61]
	global_store_dword v185, v100, s[60:61] offset:2048
	v_lshlrev_b32_e32 v104, 16, v37
	v_and_b32_e32 v108, 0xffff0000, v37
	v_fma_f32 v120, v110, v101, v118
	v_fma_f32 v121, v111, v105, v119
	v_fmac_f32_e32 v120, v112, v102
	v_fmac_f32_e32 v121, v113, v106
	v_fmac_f32_e32 v120, v114, v103
	v_fmac_f32_e32 v121, v115, v107
	v_fmac_f32_e32 v120, v116, v104
	v_fmac_f32_e32 v121, v117, v108
	v_mul_f32_e32 v122, 0xbfb8aa3b, v120
	v_mul_f32_e32 v123, 0xbfb8aa3b, v121
	v_exp_f32_e32 v122, v122
	v_exp_f32_e32 v123, v123
	s_nop 0
	v_add_f32_e32 v122, 1.0, v122
	v_add_f32_e32 v123, 1.0, v123
	v_rcp_f32_e32 v122, v122
	v_rcp_f32_e32 v123, v123
	s_nop 0
	v_mul_f32_e32 v120, v120, v122
	v_mul_f32_e32 v121, v121, v123
	v_cvt_pk_bf16_f32 v128, v120, v121
	global_store_dword v186, v128, s[60:61]
	v_lshlrev_b32_e32 v101, 16, v38
	v_and_b32_e32 v105, 0xffff0000, v38
	v_fma_f32 v120, v110, v102, v118
	v_fma_f32 v121, v111, v106, v119
	v_fmac_f32_e32 v120, v112, v103
	v_fmac_f32_e32 v121, v113, v107
	v_fmac_f32_e32 v120, v114, v104
	v_fmac_f32_e32 v121, v115, v108
	v_fmac_f32_e32 v120, v116, v101
	v_fmac_f32_e32 v121, v117, v105
	v_mul_f32_e32 v122, 0xbfb8aa3b, v120
	v_mul_f32_e32 v123, 0xbfb8aa3b, v121
	v_exp_f32_e32 v122, v122
	v_exp_f32_e32 v123, v123
	s_nop 0
	v_add_f32_e32 v122, 1.0, v122
	v_add_f32_e32 v123, 1.0, v123
	v_rcp_f32_e32 v122, v122
	v_rcp_f32_e32 v123, v123
	s_nop 0
	v_mul_f32_e32 v120, v120, v122
	v_mul_f32_e32 v121, v121, v123
	v_cvt_pk_bf16_f32 v129, v120, v121
	global_store_dword v186, v129, s[60:61] offset:2048
	v_lshlrev_b32_e32 v102, 16, v39
	v_and_b32_e32 v106, 0xffff0000, v39
	v_fma_f32 v120, v110, v103, v118
	v_fma_f32 v121, v111, v107, v119
	v_fmac_f32_e32 v120, v112, v104
	v_fmac_f32_e32 v121, v113, v108
	v_fmac_f32_e32 v120, v114, v101
	v_fmac_f32_e32 v121, v115, v105
	v_fmac_f32_e32 v120, v116, v102
	v_fmac_f32_e32 v121, v117, v106
	v_mul_f32_e32 v122, 0xbfb8aa3b, v120
	v_mul_f32_e32 v123, 0xbfb8aa3b, v121
	v_exp_f32_e32 v122, v122
	v_exp_f32_e32 v123, v123
	s_nop 0
	v_add_f32_e32 v122, 1.0, v122
	v_add_f32_e32 v123, 1.0, v123
	v_rcp_f32_e32 v122, v122
	v_rcp_f32_e32 v123, v123
	s_nop 0
	v_mul_f32_e32 v120, v120, v122
	v_mul_f32_e32 v121, v121, v123
	v_cvt_pk_bf16_f32 v128, v120, v121
	global_store_dword v187, v128, s[60:61]
	v_lshlrev_b32_e32 v103, 16, v40
	v_and_b32_e32 v107, 0xffff0000, v40
	v_fma_f32 v120, v110, v104, v118
	v_fma_f32 v121, v111, v108, v119
	v_fmac_f32_e32 v120, v112, v101
	v_fmac_f32_e32 v121, v113, v105
	v_fmac_f32_e32 v120, v114, v102
	v_fmac_f32_e32 v121, v115, v106
	v_fmac_f32_e32 v120, v116, v103
	v_fmac_f32_e32 v121, v117, v107
	v_mul_f32_e32 v122, 0xbfb8aa3b, v120
	v_mul_f32_e32 v123, 0xbfb8aa3b, v121
	v_exp_f32_e32 v122, v122
	v_exp_f32_e32 v123, v123
	s_nop 0
	v_add_f32_e32 v122, 1.0, v122
	v_add_f32_e32 v123, 1.0, v123
	v_rcp_f32_e32 v122, v122
	v_rcp_f32_e32 v123, v123
	s_nop 0
	v_mul_f32_e32 v120, v120, v122
	v_mul_f32_e32 v121, v121, v123
	v_cvt_pk_bf16_f32 v129, v120, v121
	global_store_dword v187, v129, s[60:61] offset:2048
	v_lshlrev_b32_e32 v104, 16, v41
	v_and_b32_e32 v108, 0xffff0000, v41
	v_fma_f32 v120, v110, v101, v118
	v_fma_f32 v121, v111, v105, v119
	v_fmac_f32_e32 v120, v112, v102
	v_fmac_f32_e32 v121, v113, v106
	v_fmac_f32_e32 v120, v114, v103
	v_fmac_f32_e32 v121, v115, v107
	v_fmac_f32_e32 v120, v116, v104
	v_fmac_f32_e32 v121, v117, v108
	v_mul_f32_e32 v122, 0xbfb8aa3b, v120
	v_mul_f32_e32 v123, 0xbfb8aa3b, v121
	v_exp_f32_e32 v122, v122
	v_exp_f32_e32 v123, v123
	s_nop 0
	v_add_f32_e32 v122, 1.0, v122
	v_add_f32_e32 v123, 1.0, v123
	v_rcp_f32_e32 v122, v122
	v_rcp_f32_e32 v123, v123
	s_nop 0
	v_mul_f32_e32 v120, v120, v122
	v_mul_f32_e32 v121, v121, v123
	v_cvt_pk_bf16_f32 v128, v120, v121
	global_store_dword v188, v128, s[60:61]
	v_lshlrev_b32_e32 v101, 16, v42
	v_and_b32_e32 v105, 0xffff0000, v42
	v_fma_f32 v120, v110, v102, v118
	v_fma_f32 v121, v111, v106, v119
	v_fmac_f32_e32 v120, v112, v103
	v_fmac_f32_e32 v121, v113, v107
	v_fmac_f32_e32 v120, v114, v104
	v_fmac_f32_e32 v121, v115, v108
	v_fmac_f32_e32 v120, v116, v101
	v_fmac_f32_e32 v121, v117, v105
	v_mul_f32_e32 v122, 0xbfb8aa3b, v120
	v_mul_f32_e32 v123, 0xbfb8aa3b, v121
	v_exp_f32_e32 v122, v122
	v_exp_f32_e32 v123, v123
	s_nop 0
	v_add_f32_e32 v122, 1.0, v122
	v_add_f32_e32 v123, 1.0, v123
	v_rcp_f32_e32 v122, v122
	v_rcp_f32_e32 v123, v123
	s_nop 0
	v_mul_f32_e32 v120, v120, v122
	v_mul_f32_e32 v121, v121, v123
	v_cvt_pk_bf16_f32 v129, v120, v121
	global_store_dword v188, v129, s[60:61] offset:2048
	v_lshlrev_b32_e32 v102, 16, v43
	v_and_b32_e32 v106, 0xffff0000, v43
	v_fma_f32 v120, v110, v103, v118
	v_fma_f32 v121, v111, v107, v119
	v_fmac_f32_e32 v120, v112, v104
	v_fmac_f32_e32 v121, v113, v108
	v_fmac_f32_e32 v120, v114, v101
	v_fmac_f32_e32 v121, v115, v105
	v_fmac_f32_e32 v120, v116, v102
	v_fmac_f32_e32 v121, v117, v106
	v_mul_f32_e32 v122, 0xbfb8aa3b, v120
	v_mul_f32_e32 v123, 0xbfb8aa3b, v121
	v_exp_f32_e32 v122, v122
	v_exp_f32_e32 v123, v123
	s_nop 0
	v_add_f32_e32 v122, 1.0, v122
	v_add_f32_e32 v123, 1.0, v123
	v_rcp_f32_e32 v122, v122
	v_rcp_f32_e32 v123, v123
	s_nop 0
	v_mul_f32_e32 v120, v120, v122
	v_mul_f32_e32 v121, v121, v123
	v_cvt_pk_bf16_f32 v128, v120, v121
	global_store_dword v189, v128, s[60:61]
	v_lshlrev_b32_e32 v103, 16, v44
	v_and_b32_e32 v107, 0xffff0000, v44
	v_fma_f32 v120, v110, v104, v118
	v_fma_f32 v121, v111, v108, v119
	v_fmac_f32_e32 v120, v112, v101
	v_fmac_f32_e32 v121, v113, v105
	v_fmac_f32_e32 v120, v114, v102
	v_fmac_f32_e32 v121, v115, v106
	v_fmac_f32_e32 v120, v116, v103
	v_fmac_f32_e32 v121, v117, v107
	v_mul_f32_e32 v122, 0xbfb8aa3b, v120
	v_mul_f32_e32 v123, 0xbfb8aa3b, v121
	v_exp_f32_e32 v122, v122
	v_exp_f32_e32 v123, v123
	s_nop 0
	v_add_f32_e32 v122, 1.0, v122
	v_add_f32_e32 v123, 1.0, v123
	v_rcp_f32_e32 v122, v122
	v_rcp_f32_e32 v123, v123
	s_nop 0
	v_mul_f32_e32 v120, v120, v122
	v_mul_f32_e32 v121, v121, v123
	v_cvt_pk_bf16_f32 v129, v120, v121
	global_store_dword v189, v129, s[60:61] offset:2048
	v_lshlrev_b32_e32 v104, 16, v45
	v_and_b32_e32 v108, 0xffff0000, v45
	v_fma_f32 v120, v110, v101, v118
	v_fma_f32 v121, v111, v105, v119
	v_fmac_f32_e32 v120, v112, v102
	v_fmac_f32_e32 v121, v113, v106
	v_fmac_f32_e32 v120, v114, v103
	v_fmac_f32_e32 v121, v115, v107
	v_fmac_f32_e32 v120, v116, v104
	v_fmac_f32_e32 v121, v117, v108
	v_mul_f32_e32 v122, 0xbfb8aa3b, v120
	v_mul_f32_e32 v123, 0xbfb8aa3b, v121
	v_exp_f32_e32 v122, v122
	v_exp_f32_e32 v123, v123
	s_nop 0
	v_add_f32_e32 v122, 1.0, v122
	v_add_f32_e32 v123, 1.0, v123
	v_rcp_f32_e32 v122, v122
	v_rcp_f32_e32 v123, v123
	s_nop 0
	v_mul_f32_e32 v120, v120, v122
	v_mul_f32_e32 v121, v121, v123
	v_cvt_pk_bf16_f32 v128, v120, v121
	global_store_dword v190, v128, s[60:61]
	v_lshlrev_b32_e32 v101, 16, v46
	v_and_b32_e32 v105, 0xffff0000, v46
	v_fma_f32 v120, v110, v102, v118
	v_fma_f32 v121, v111, v106, v119
	v_fmac_f32_e32 v120, v112, v103
	v_fmac_f32_e32 v121, v113, v107
	v_fmac_f32_e32 v120, v114, v104
	v_fmac_f32_e32 v121, v115, v108
	v_fmac_f32_e32 v120, v116, v101
	v_fmac_f32_e32 v121, v117, v105
	v_mul_f32_e32 v122, 0xbfb8aa3b, v120
	v_mul_f32_e32 v123, 0xbfb8aa3b, v121
	v_exp_f32_e32 v122, v122
	v_exp_f32_e32 v123, v123
	s_nop 0
	v_add_f32_e32 v122, 1.0, v122
	v_add_f32_e32 v123, 1.0, v123
	v_rcp_f32_e32 v122, v122
	v_rcp_f32_e32 v123, v123
	s_nop 0
	v_mul_f32_e32 v120, v120, v122
	v_mul_f32_e32 v121, v121, v123
	v_cvt_pk_bf16_f32 v129, v120, v121
	global_store_dword v190, v129, s[60:61] offset:2048
	v_lshlrev_b32_e32 v102, 16, v47
	v_and_b32_e32 v106, 0xffff0000, v47
	v_fma_f32 v120, v110, v103, v118
	v_fma_f32 v121, v111, v107, v119
	v_fmac_f32_e32 v120, v112, v104
	v_fmac_f32_e32 v121, v113, v108
	v_fmac_f32_e32 v120, v114, v101
	v_fmac_f32_e32 v121, v115, v105
	v_fmac_f32_e32 v120, v116, v102
	v_fmac_f32_e32 v121, v117, v106
	v_mul_f32_e32 v122, 0xbfb8aa3b, v120
	v_mul_f32_e32 v123, 0xbfb8aa3b, v121
	v_exp_f32_e32 v122, v122
	v_exp_f32_e32 v123, v123
	s_nop 0
	v_add_f32_e32 v122, 1.0, v122
	v_add_f32_e32 v123, 1.0, v123
	v_rcp_f32_e32 v122, v122
	v_rcp_f32_e32 v123, v123
	s_nop 0
	v_mul_f32_e32 v120, v120, v122
	v_mul_f32_e32 v121, v121, v123
	v_cvt_pk_bf16_f32 v128, v120, v121
	global_store_dword v191, v128, s[60:61]
	v_lshlrev_b32_e32 v103, 16, v48
	v_and_b32_e32 v107, 0xffff0000, v48
	v_fma_f32 v120, v110, v104, v118
	v_fma_f32 v121, v111, v108, v119
	v_fmac_f32_e32 v120, v112, v101
	v_fmac_f32_e32 v121, v113, v105
	v_fmac_f32_e32 v120, v114, v102
	v_fmac_f32_e32 v121, v115, v106
	v_fmac_f32_e32 v120, v116, v103
	v_fmac_f32_e32 v121, v117, v107
	v_mul_f32_e32 v122, 0xbfb8aa3b, v120
	v_mul_f32_e32 v123, 0xbfb8aa3b, v121
	v_exp_f32_e32 v122, v122
	v_exp_f32_e32 v123, v123
	s_nop 0
	v_add_f32_e32 v122, 1.0, v122
	v_add_f32_e32 v123, 1.0, v123
	v_rcp_f32_e32 v122, v122
	v_rcp_f32_e32 v123, v123
	s_nop 0
	v_mul_f32_e32 v120, v120, v122
	v_mul_f32_e32 v121, v121, v123
	v_cvt_pk_bf16_f32 v129, v120, v121
	global_store_dword v191, v129, s[60:61] offset:2048
	v_lshlrev_b32_e32 v104, 16, v49
	v_and_b32_e32 v108, 0xffff0000, v49
	v_fma_f32 v120, v110, v101, v118
	v_fma_f32 v121, v111, v105, v119
	v_fmac_f32_e32 v120, v112, v102
	v_fmac_f32_e32 v121, v113, v106
	v_fmac_f32_e32 v120, v114, v103
	v_fmac_f32_e32 v121, v115, v107
	v_fmac_f32_e32 v120, v116, v104
	v_fmac_f32_e32 v121, v117, v108
	v_mul_f32_e32 v122, 0xbfb8aa3b, v120
	v_mul_f32_e32 v123, 0xbfb8aa3b, v121
	v_exp_f32_e32 v122, v122
	v_exp_f32_e32 v123, v123
	s_nop 0
	v_add_f32_e32 v122, 1.0, v122
	v_add_f32_e32 v123, 1.0, v123
	v_rcp_f32_e32 v122, v122
	v_rcp_f32_e32 v123, v123
	s_nop 0
	v_mul_f32_e32 v120, v120, v122
	v_mul_f32_e32 v121, v121, v123
	v_cvt_pk_bf16_f32 v128, v120, v121
	global_store_dword v192, v128, s[60:61]
	v_lshlrev_b32_e32 v101, 16, v50
	v_and_b32_e32 v105, 0xffff0000, v50
	v_fma_f32 v120, v110, v102, v118
	v_fma_f32 v121, v111, v106, v119
	v_fmac_f32_e32 v120, v112, v103
	v_fmac_f32_e32 v121, v113, v107
	v_fmac_f32_e32 v120, v114, v104
	v_fmac_f32_e32 v121, v115, v108
	v_fmac_f32_e32 v120, v116, v101
	v_fmac_f32_e32 v121, v117, v105
	v_mul_f32_e32 v122, 0xbfb8aa3b, v120
	v_mul_f32_e32 v123, 0xbfb8aa3b, v121
	v_exp_f32_e32 v122, v122
	v_exp_f32_e32 v123, v123
	s_nop 0
	v_add_f32_e32 v122, 1.0, v122
	v_add_f32_e32 v123, 1.0, v123
	v_rcp_f32_e32 v122, v122
	v_rcp_f32_e32 v123, v123
	s_nop 0
	v_mul_f32_e32 v120, v120, v122
	v_mul_f32_e32 v121, v121, v123
	v_cvt_pk_bf16_f32 v129, v120, v121
	global_store_dword v192, v129, s[60:61] offset:2048
	v_lshlrev_b32_e32 v102, 16, v51
	v_and_b32_e32 v106, 0xffff0000, v51
	v_fma_f32 v120, v110, v103, v118
	v_fma_f32 v121, v111, v107, v119
	v_fmac_f32_e32 v120, v112, v104
	v_fmac_f32_e32 v121, v113, v108
	v_fmac_f32_e32 v120, v114, v101
	v_fmac_f32_e32 v121, v115, v105
	v_fmac_f32_e32 v120, v116, v102
	v_fmac_f32_e32 v121, v117, v106
	v_mul_f32_e32 v122, 0xbfb8aa3b, v120
	v_mul_f32_e32 v123, 0xbfb8aa3b, v121
	v_exp_f32_e32 v122, v122
	v_exp_f32_e32 v123, v123
	s_nop 0
	v_add_f32_e32 v122, 1.0, v122
	v_add_f32_e32 v123, 1.0, v123
	v_rcp_f32_e32 v122, v122
	v_rcp_f32_e32 v123, v123
	s_nop 0
	v_mul_f32_e32 v120, v120, v122
	v_mul_f32_e32 v121, v121, v123
	v_cvt_pk_bf16_f32 v128, v120, v121
	global_store_dword v193, v128, s[60:61]
	v_lshlrev_b32_e32 v103, 16, v52
	v_and_b32_e32 v107, 0xffff0000, v52
	v_fma_f32 v120, v110, v104, v118
	v_fma_f32 v121, v111, v108, v119
	v_fmac_f32_e32 v120, v112, v101
	v_fmac_f32_e32 v121, v113, v105
	v_fmac_f32_e32 v120, v114, v102
	v_fmac_f32_e32 v121, v115, v106
	v_fmac_f32_e32 v120, v116, v103
	v_fmac_f32_e32 v121, v117, v107
	v_mul_f32_e32 v122, 0xbfb8aa3b, v120
	v_mul_f32_e32 v123, 0xbfb8aa3b, v121
	v_exp_f32_e32 v122, v122
	v_exp_f32_e32 v123, v123
	s_nop 0
	v_add_f32_e32 v122, 1.0, v122
	v_add_f32_e32 v123, 1.0, v123
	v_rcp_f32_e32 v122, v122
	v_rcp_f32_e32 v123, v123
	s_nop 0
	v_mul_f32_e32 v120, v120, v122
	v_mul_f32_e32 v121, v121, v123
	v_cvt_pk_bf16_f32 v129, v120, v121
	global_store_dword v193, v129, s[60:61] offset:2048
	v_lshlrev_b32_e32 v104, 16, v53
	v_and_b32_e32 v108, 0xffff0000, v53
	v_fma_f32 v120, v110, v101, v118
	v_fma_f32 v121, v111, v105, v119
	v_fmac_f32_e32 v120, v112, v102
	v_fmac_f32_e32 v121, v113, v106
	v_fmac_f32_e32 v120, v114, v103
	v_fmac_f32_e32 v121, v115, v107
	v_fmac_f32_e32 v120, v116, v104
	v_fmac_f32_e32 v121, v117, v108
	v_mul_f32_e32 v122, 0xbfb8aa3b, v120
	v_mul_f32_e32 v123, 0xbfb8aa3b, v121
	v_exp_f32_e32 v122, v122
	v_exp_f32_e32 v123, v123
	s_nop 0
	v_add_f32_e32 v122, 1.0, v122
	v_add_f32_e32 v123, 1.0, v123
	v_rcp_f32_e32 v122, v122
	v_rcp_f32_e32 v123, v123
	s_nop 0
	v_mul_f32_e32 v120, v120, v122
	v_mul_f32_e32 v121, v121, v123
	v_cvt_pk_bf16_f32 v128, v120, v121
	global_store_dword v194, v128, s[60:61]
	v_lshlrev_b32_e32 v101, 16, v54
	v_and_b32_e32 v105, 0xffff0000, v54
	v_fma_f32 v120, v110, v102, v118
	v_fma_f32 v121, v111, v106, v119
	v_fmac_f32_e32 v120, v112, v103
	v_fmac_f32_e32 v121, v113, v107
	v_fmac_f32_e32 v120, v114, v104
	v_fmac_f32_e32 v121, v115, v108
	v_fmac_f32_e32 v120, v116, v101
	v_fmac_f32_e32 v121, v117, v105
	v_mul_f32_e32 v122, 0xbfb8aa3b, v120
	v_mul_f32_e32 v123, 0xbfb8aa3b, v121
	v_exp_f32_e32 v122, v122
	v_exp_f32_e32 v123, v123
	s_nop 0
	v_add_f32_e32 v122, 1.0, v122
	v_add_f32_e32 v123, 1.0, v123
	v_rcp_f32_e32 v122, v122
	v_rcp_f32_e32 v123, v123
	s_nop 0
	v_mul_f32_e32 v120, v120, v122
	v_mul_f32_e32 v121, v121, v123
	v_cvt_pk_bf16_f32 v129, v120, v121
	global_store_dword v194, v129, s[60:61] offset:2048
	v_lshlrev_b32_e32 v102, 16, v55
	v_and_b32_e32 v106, 0xffff0000, v55
	v_fma_f32 v120, v110, v103, v118
	v_fma_f32 v121, v111, v107, v119
	v_fmac_f32_e32 v120, v112, v104
	v_fmac_f32_e32 v121, v113, v108
	v_fmac_f32_e32 v120, v114, v101
	v_fmac_f32_e32 v121, v115, v105
	v_fmac_f32_e32 v120, v116, v102
	v_fmac_f32_e32 v121, v117, v106
	v_mul_f32_e32 v122, 0xbfb8aa3b, v120
	v_mul_f32_e32 v123, 0xbfb8aa3b, v121
	v_exp_f32_e32 v122, v122
	v_exp_f32_e32 v123, v123
	s_nop 0
	v_add_f32_e32 v122, 1.0, v122
	v_add_f32_e32 v123, 1.0, v123
	v_rcp_f32_e32 v122, v122
	v_rcp_f32_e32 v123, v123
	s_nop 0
	v_mul_f32_e32 v120, v120, v122
	v_mul_f32_e32 v121, v121, v123
	v_cvt_pk_bf16_f32 v128, v120, v121
	global_store_dword v195, v128, s[60:61]
	v_lshlrev_b32_e32 v103, 16, v56
	v_and_b32_e32 v107, 0xffff0000, v56
	v_fma_f32 v120, v110, v104, v118
	v_fma_f32 v121, v111, v108, v119
	v_fmac_f32_e32 v120, v112, v101
	v_fmac_f32_e32 v121, v113, v105
	v_fmac_f32_e32 v120, v114, v102
	v_fmac_f32_e32 v121, v115, v106
	v_fmac_f32_e32 v120, v116, v103
	v_fmac_f32_e32 v121, v117, v107
	v_mul_f32_e32 v122, 0xbfb8aa3b, v120
	v_mul_f32_e32 v123, 0xbfb8aa3b, v121
	v_exp_f32_e32 v122, v122
	v_exp_f32_e32 v123, v123
	s_nop 0
	v_add_f32_e32 v122, 1.0, v122
	v_add_f32_e32 v123, 1.0, v123
	v_rcp_f32_e32 v122, v122
	v_rcp_f32_e32 v123, v123
	s_nop 0
	v_mul_f32_e32 v120, v120, v122
	v_mul_f32_e32 v121, v121, v123
	v_cvt_pk_bf16_f32 v129, v120, v121
	global_store_dword v195, v129, s[60:61] offset:2048
	v_lshlrev_b32_e32 v104, 16, v57
	v_and_b32_e32 v108, 0xffff0000, v57
	v_fma_f32 v120, v110, v101, v118
	v_fma_f32 v121, v111, v105, v119
	v_fmac_f32_e32 v120, v112, v102
	v_fmac_f32_e32 v121, v113, v106
	v_fmac_f32_e32 v120, v114, v103
	v_fmac_f32_e32 v121, v115, v107
	v_fmac_f32_e32 v120, v116, v104
	v_fmac_f32_e32 v121, v117, v108
	v_mul_f32_e32 v122, 0xbfb8aa3b, v120
	v_mul_f32_e32 v123, 0xbfb8aa3b, v121
	v_exp_f32_e32 v122, v122
	v_exp_f32_e32 v123, v123
	s_nop 0
	v_add_f32_e32 v122, 1.0, v122
	v_add_f32_e32 v123, 1.0, v123
	v_rcp_f32_e32 v122, v122
	v_rcp_f32_e32 v123, v123
	s_nop 0
	v_mul_f32_e32 v120, v120, v122
	v_mul_f32_e32 v121, v121, v123
	v_cvt_pk_bf16_f32 v128, v120, v121
	global_store_dword v196, v128, s[60:61]
	v_lshlrev_b32_e32 v101, 16, v58
	v_and_b32_e32 v105, 0xffff0000, v58
	v_fma_f32 v120, v110, v102, v118
	v_fma_f32 v121, v111, v106, v119
	v_fmac_f32_e32 v120, v112, v103
	v_fmac_f32_e32 v121, v113, v107
	v_fmac_f32_e32 v120, v114, v104
	v_fmac_f32_e32 v121, v115, v108
	v_fmac_f32_e32 v120, v116, v101
	v_fmac_f32_e32 v121, v117, v105
	v_mul_f32_e32 v122, 0xbfb8aa3b, v120
	v_mul_f32_e32 v123, 0xbfb8aa3b, v121
	v_exp_f32_e32 v122, v122
	v_exp_f32_e32 v123, v123
	s_nop 0
	v_add_f32_e32 v122, 1.0, v122
	v_add_f32_e32 v123, 1.0, v123
	v_rcp_f32_e32 v122, v122
	v_rcp_f32_e32 v123, v123
	s_nop 0
	v_mul_f32_e32 v120, v120, v122
	v_mul_f32_e32 v121, v121, v123
	v_cvt_pk_bf16_f32 v129, v120, v121
	global_store_dword v196, v129, s[60:61] offset:2048
	v_lshlrev_b32_e32 v102, 16, v59
	v_and_b32_e32 v106, 0xffff0000, v59
	v_fma_f32 v120, v110, v103, v118
	v_fma_f32 v121, v111, v107, v119
	v_fmac_f32_e32 v120, v112, v104
	v_fmac_f32_e32 v121, v113, v108
	v_fmac_f32_e32 v120, v114, v101
	v_fmac_f32_e32 v121, v115, v105
	v_fmac_f32_e32 v120, v116, v102
	v_fmac_f32_e32 v121, v117, v106
	v_mul_f32_e32 v122, 0xbfb8aa3b, v120
	v_mul_f32_e32 v123, 0xbfb8aa3b, v121
	v_exp_f32_e32 v122, v122
	v_exp_f32_e32 v123, v123
	s_nop 0
	v_add_f32_e32 v122, 1.0, v122
	v_add_f32_e32 v123, 1.0, v123
	v_rcp_f32_e32 v122, v122
	v_rcp_f32_e32 v123, v123
	s_nop 0
	v_mul_f32_e32 v120, v120, v122
	v_mul_f32_e32 v121, v121, v123
	v_cvt_pk_bf16_f32 v128, v120, v121
	global_store_dword v197, v128, s[60:61]
	v_lshlrev_b32_e32 v103, 16, v60
	v_and_b32_e32 v107, 0xffff0000, v60
	v_fma_f32 v120, v110, v104, v118
	v_fma_f32 v121, v111, v108, v119
	v_fmac_f32_e32 v120, v112, v101
	v_fmac_f32_e32 v121, v113, v105
	v_fmac_f32_e32 v120, v114, v102
	v_fmac_f32_e32 v121, v115, v106
	v_fmac_f32_e32 v120, v116, v103
	v_fmac_f32_e32 v121, v117, v107
	v_mul_f32_e32 v122, 0xbfb8aa3b, v120
	v_mul_f32_e32 v123, 0xbfb8aa3b, v121
	v_exp_f32_e32 v122, v122
	v_exp_f32_e32 v123, v123
	s_nop 0
	v_add_f32_e32 v122, 1.0, v122
	v_add_f32_e32 v123, 1.0, v123
	v_rcp_f32_e32 v122, v122
	v_rcp_f32_e32 v123, v123
	s_nop 0
	v_mul_f32_e32 v120, v120, v122
	v_mul_f32_e32 v121, v121, v123
	v_cvt_pk_bf16_f32 v129, v120, v121
	global_store_dword v197, v129, s[60:61] offset:2048
	v_lshlrev_b32_e32 v104, 16, v61
	v_and_b32_e32 v108, 0xffff0000, v61
	v_fma_f32 v120, v110, v101, v118
	v_fma_f32 v121, v111, v105, v119
	v_fmac_f32_e32 v120, v112, v102
	v_fmac_f32_e32 v121, v113, v106
	v_fmac_f32_e32 v120, v114, v103
	v_fmac_f32_e32 v121, v115, v107
	v_fmac_f32_e32 v120, v116, v104
	v_fmac_f32_e32 v121, v117, v108
	v_mul_f32_e32 v122, 0xbfb8aa3b, v120
	v_mul_f32_e32 v123, 0xbfb8aa3b, v121
	v_exp_f32_e32 v122, v122
	v_exp_f32_e32 v123, v123
	s_nop 0
	v_add_f32_e32 v122, 1.0, v122
	v_add_f32_e32 v123, 1.0, v123
	v_rcp_f32_e32 v122, v122
	v_rcp_f32_e32 v123, v123
	s_nop 0
	v_mul_f32_e32 v120, v120, v122
	v_mul_f32_e32 v121, v121, v123
	v_cvt_pk_bf16_f32 v128, v120, v121
	global_store_dword v198, v128, s[60:61]
	v_lshlrev_b32_e32 v101, 16, v62
	v_and_b32_e32 v105, 0xffff0000, v62
	v_fma_f32 v120, v110, v102, v118
	v_fma_f32 v121, v111, v106, v119
	v_fmac_f32_e32 v120, v112, v103
	v_fmac_f32_e32 v121, v113, v107
	v_fmac_f32_e32 v120, v114, v104
	v_fmac_f32_e32 v121, v115, v108
	v_fmac_f32_e32 v120, v116, v101
	v_fmac_f32_e32 v121, v117, v105
	v_mul_f32_e32 v122, 0xbfb8aa3b, v120
	v_mul_f32_e32 v123, 0xbfb8aa3b, v121
	v_exp_f32_e32 v122, v122
	v_exp_f32_e32 v123, v123
	s_nop 0
	v_add_f32_e32 v122, 1.0, v122
	v_add_f32_e32 v123, 1.0, v123
	v_rcp_f32_e32 v122, v122
	v_rcp_f32_e32 v123, v123
	s_nop 0
	v_mul_f32_e32 v120, v120, v122
	v_mul_f32_e32 v121, v121, v123
	v_cvt_pk_bf16_f32 v129, v120, v121
	global_store_dword v198, v129, s[60:61] offset:2048
	v_lshlrev_b32_e32 v102, 16, v63
	v_and_b32_e32 v106, 0xffff0000, v63
	v_fma_f32 v120, v110, v103, v118
	v_fma_f32 v121, v111, v107, v119
	v_fmac_f32_e32 v120, v112, v104
	v_fmac_f32_e32 v121, v113, v108
	v_fmac_f32_e32 v120, v114, v101
	v_fmac_f32_e32 v121, v115, v105
	v_fmac_f32_e32 v120, v116, v102
	v_fmac_f32_e32 v121, v117, v106
	v_mul_f32_e32 v122, 0xbfb8aa3b, v120
	v_mul_f32_e32 v123, 0xbfb8aa3b, v121
	v_exp_f32_e32 v122, v122
	v_exp_f32_e32 v123, v123
	s_nop 0
	v_add_f32_e32 v122, 1.0, v122
	v_add_f32_e32 v123, 1.0, v123
	v_rcp_f32_e32 v122, v122
	v_rcp_f32_e32 v123, v123
	s_nop 0
	v_mul_f32_e32 v120, v120, v122
	v_mul_f32_e32 v121, v121, v123
	v_cvt_pk_bf16_f32 v128, v120, v121
	global_store_dword v199, v128, s[60:61]
	v_lshlrev_b32_e32 v103, 16, v64
	v_and_b32_e32 v107, 0xffff0000, v64
	v_fma_f32 v120, v110, v104, v118
	v_fma_f32 v121, v111, v108, v119
	v_fmac_f32_e32 v120, v112, v101
	v_fmac_f32_e32 v121, v113, v105
	v_fmac_f32_e32 v120, v114, v102
	v_fmac_f32_e32 v121, v115, v106
	v_fmac_f32_e32 v120, v116, v103
	v_fmac_f32_e32 v121, v117, v107
	v_mul_f32_e32 v122, 0xbfb8aa3b, v120
	v_mul_f32_e32 v123, 0xbfb8aa3b, v121
	v_exp_f32_e32 v122, v122
	v_exp_f32_e32 v123, v123
	s_nop 0
	v_add_f32_e32 v122, 1.0, v122
	v_add_f32_e32 v123, 1.0, v123
	v_rcp_f32_e32 v122, v122
	v_rcp_f32_e32 v123, v123
	s_nop 0
	v_mul_f32_e32 v120, v120, v122
	v_mul_f32_e32 v121, v121, v123
	v_cvt_pk_bf16_f32 v129, v120, v121
	global_store_dword v199, v129, s[60:61] offset:2048
	v_lshlrev_b32_e32 v104, 16, v65
	v_and_b32_e32 v108, 0xffff0000, v65
	v_fma_f32 v120, v110, v101, v118
	v_fma_f32 v121, v111, v105, v119
	v_fmac_f32_e32 v120, v112, v102
	v_fmac_f32_e32 v121, v113, v106
	v_fmac_f32_e32 v120, v114, v103
	v_fmac_f32_e32 v121, v115, v107
	v_fmac_f32_e32 v120, v116, v104
	v_fmac_f32_e32 v121, v117, v108
	v_mul_f32_e32 v122, 0xbfb8aa3b, v120
	v_mul_f32_e32 v123, 0xbfb8aa3b, v121
	v_exp_f32_e32 v122, v122
	v_exp_f32_e32 v123, v123
	s_nop 0
	v_add_f32_e32 v122, 1.0, v122
	v_add_f32_e32 v123, 1.0, v123
	v_rcp_f32_e32 v122, v122
	v_rcp_f32_e32 v123, v123
	s_nop 0
	v_mul_f32_e32 v120, v120, v122
	v_mul_f32_e32 v121, v121, v123
	v_cvt_pk_bf16_f32 v128, v120, v121
	global_store_dword v200, v128, s[60:61]
	v_lshlrev_b32_e32 v101, 16, v66
	v_and_b32_e32 v105, 0xffff0000, v66
	v_fma_f32 v120, v110, v102, v118
	v_fma_f32 v121, v111, v106, v119
	v_fmac_f32_e32 v120, v112, v103
	v_fmac_f32_e32 v121, v113, v107
	v_fmac_f32_e32 v120, v114, v104
	v_fmac_f32_e32 v121, v115, v108
	v_fmac_f32_e32 v120, v116, v101
	v_fmac_f32_e32 v121, v117, v105
	v_mul_f32_e32 v122, 0xbfb8aa3b, v120
	v_mul_f32_e32 v123, 0xbfb8aa3b, v121
	v_exp_f32_e32 v122, v122
	v_exp_f32_e32 v123, v123
	s_nop 0
	v_add_f32_e32 v122, 1.0, v122
	v_add_f32_e32 v123, 1.0, v123
	v_rcp_f32_e32 v122, v122
	v_rcp_f32_e32 v123, v123
	s_nop 0
	v_mul_f32_e32 v120, v120, v122
	v_mul_f32_e32 v121, v121, v123
	v_cvt_pk_bf16_f32 v129, v120, v121
	global_store_dword v200, v129, s[60:61] offset:2048
	v_lshlrev_b32_e32 v102, 16, v67
	v_and_b32_e32 v106, 0xffff0000, v67
	v_fma_f32 v120, v110, v103, v118
	v_fma_f32 v121, v111, v107, v119
	v_fmac_f32_e32 v120, v112, v104
	v_fmac_f32_e32 v121, v113, v108
	v_fmac_f32_e32 v120, v114, v101
	v_fmac_f32_e32 v121, v115, v105
	v_fmac_f32_e32 v120, v116, v102
	v_fmac_f32_e32 v121, v117, v106
	v_mul_f32_e32 v122, 0xbfb8aa3b, v120
	v_mul_f32_e32 v123, 0xbfb8aa3b, v121
	v_exp_f32_e32 v122, v122
	v_exp_f32_e32 v123, v123
	s_nop 0
	v_add_f32_e32 v122, 1.0, v122
	v_add_f32_e32 v123, 1.0, v123
	v_rcp_f32_e32 v122, v122
	v_rcp_f32_e32 v123, v123
	s_nop 0
	v_mul_f32_e32 v120, v120, v122
	v_mul_f32_e32 v121, v121, v123
	v_cvt_pk_bf16_f32 v128, v120, v121
	global_store_dword v201, v128, s[60:61]
	v_lshlrev_b32_e32 v103, 16, v68
	v_and_b32_e32 v107, 0xffff0000, v68
	v_fma_f32 v120, v110, v104, v118
	v_fma_f32 v121, v111, v108, v119
	v_fmac_f32_e32 v120, v112, v101
	v_fmac_f32_e32 v121, v113, v105
	v_fmac_f32_e32 v120, v114, v102
	v_fmac_f32_e32 v121, v115, v106
	v_fmac_f32_e32 v120, v116, v103
	v_fmac_f32_e32 v121, v117, v107
	v_mul_f32_e32 v122, 0xbfb8aa3b, v120
	v_mul_f32_e32 v123, 0xbfb8aa3b, v121
	v_exp_f32_e32 v122, v122
	v_exp_f32_e32 v123, v123
	s_nop 0
	v_add_f32_e32 v122, 1.0, v122
	v_add_f32_e32 v123, 1.0, v123
	v_rcp_f32_e32 v122, v122
	v_rcp_f32_e32 v123, v123
	s_nop 0
	v_mul_f32_e32 v120, v120, v122
	v_mul_f32_e32 v121, v121, v123
	v_cvt_pk_bf16_f32 v129, v120, v121
	global_store_dword v201, v129, s[60:61] offset:2048
	v_add_u32_e32 v132, s36, v132
	v_cmp_lt_i32_e32 vcc, 0x1ffff, v132
	s_or_b64 s[14:15], vcc, s[14:15]
	s_andn2_b64 exec, exec, s[14:15]
	s_cbranch_execnz .LBB0_369
